# L0X sample rows de-serialised; P0 gain prefetch; decode-gate loads batched; W_out residual epilogue with all loads in flight
# speedup vs baseline: 1.0508x; 1.0201x over previous
; __device__ __forceinline__ bool p0_decode(int it, const P0Src& t, int wid, int lane, P0Desc& d) {
;     if (it >= 2 * P0_I_L) return false;
;     const int l = it / P0_I_L; int rr = it - l * P0_I_L; const float* W; int ldw, nv, K, blk, kb, dg; bf16_t* WT; bool perm; const float* gk = nullptr;
;     if (rr < P0_I_IN) { blk = rr >> 5; kb = rr & 31; const int sg = blk * 8 + wid; W = t.w_in + (size_t)l * DM * INC; ldw = INC; nv = INC; K = DM; WT = t.WT_IN + (size_t)l * INP * DM; gk = t.g_mix + (size_t)l * DM;
;         if (sg < 32) { dg = 64 + sg; perm = true; } else if (sg < 64) { const int q = sg - 32; dg = (q >> 2) * 8 + (q & 3); perm = true; } else if (sg < 96) { const int q = sg - 64; dg = (q >> 2) * 8 + 4 + (q & 3); perm = true; }
;         else { dg = sg; perm = sg < 192; } }
;     else if ((rr -= P0_I_IN) < P0_I_OUT) { blk = rr >> 5; kb = rr & 31; dg = blk * 8 + wid; perm = true; W = t.w_out + (size_t)l * DM * DM; ldw = DM; nv = DM; K = DM; WT = t.WT_OUT + (size_t)l * DM * DM; }
;     else if ((rr -= P0_I_OUT) < P0_I_UP) { blk = rr >> 5; kb = rr & 31; const int sg = blk * 8 + wid; perm = true; W = t.w_up + (size_t)l * DM * UPN; ldw = UPN; nv = UPN; K = DM; WT = t.WT_UP + (size_t)l * UPN * DM; gk = t.g_ffn + (size_t)l * DM;
;         if (sg < 176) dg = (sg >> 2) * 8 + (sg & 3); else { const int q = sg - 176; dg = (q >> 2) * 8 + 4 + (q & 3); } }
;     else { rr -= P0_I_UP; blk = rr / 88; kb = rr - blk * 88; dg = blk * 8 + wid; perm = true; W = t.w_down + (size_t)l * DFF * DM; ldw = DM; nv = DM; K = DFF; WT = t.WT_DN + (size_t)l * DM * DFF; }
;     const int k0 = 64 * kb, c = blk * 256 + 4 * lane;
;     d.ok = c < nv; d.src = W + (size_t)(k0 + wid * 8) * ldw + c; d.ldw = (size_t)ldw; d.gk = gk ? gk + k0 + wid * 8 : nullptr; d.dst = WT + (size_t)(dg * 32) * K + k0; d.K = K; d.perm = perm; return true;
; }
; __global__ void __launch_bounds__(NTHR, 2) fwd_kernel(Args a) {
;     ...
;         { const P0Src ts{w_in, w_out, w_up, w_down, norm_mix_g, norm_ffn_g, WT_IN, WT_OUT, WT_UP, WT_DN}; LAS float* T = (LAS float*)lds;
;           int it = bid; P0Desc dc, dn; f32x4 tv[8];
;           bool have = p0_decode(it, ts, wid, lane, dc); if (have) p0_load(dc, tv);
;           while (have) {
;               p0_to_lds(dc, tv, T, wid, lane);
;               __syncthreads();
;               const bool hn = p0_decode(it + G, ts, wid, lane, dn); if (hn) p0_load(dn, tv);
.LBB0_82:
	s_and_b64 vcc, exec, s[6:7]
	v_lshlrev_b32_e32 v35, 3, v32
	s_cbranch_vccnz .LBB0_149
	v_lshrrev_b32_e32 v34, 3, v32
	v_lshrrev_b32_e32 v38, 2, v32
	v_and_b32_e32 v42, 8, v38
	v_or_b32_e32 v38, 8, v34
	v_bfe_u32 v40, v32, 3, 2
	v_lshlrev_b32_e32 v45, 1, v38
	s_lshl_b32 s7, s33, 7
	v_and_or_b32 v47, v45, 24, v40
	v_or_b32_e32 v45, 4, v34
	s_mov_b32 s23, 0
	s_add_i32 s7, s7, 0
	v_or_b32_e32 v43, v42, v40
	v_or_b32_e32 v48, v42, v45
	v_or_b32_e32 v42, 24, v34
	v_lshl_add_u32 v44, v32, 4, 0
	s_mul_i32 s6, s33, 0x2020
	s_bfe_u32 s52, s36, 0x20006
	s_lshl_b32 s24, s33, 3
	v_and_b32_e32 v36, 56, v35
	s_movk_i32 s22, 0x404
	v_mov_b32_e32 v37, s7
	v_lshlrev_b32_e32 v46, 1, v42
	s_add_i32 s54, s82, 0xfffff660
	v_lshlrev_b32_e32 v39, 2, v32
	s_ashr_i32 s25, s24, 31
	v_mad_u32_u24 v41, v36, s22, v37
	v_mov_b32_e32 v37, 0
	v_or_b32_e32 v40, 16, v34
	v_and_or_b32 v49, v46, 24, v45
	s_or_b32 s53, s52, 4
	s_add_i32 s55, s54, s62
	v_lshlrev_b32_e32 v36, 1, v36
	v_add_u32_e32 v50, s6, v44
	s_mov_b32 s43, s62
	s_cmp_eq_u64 s[26:27], 0
	s_cbranch_scc1 .Lp0_nogain_a
	global_load_dwordx4 v[248:251], v37, s[26:27]
	global_load_dwordx4 v[252:255], v37, s[26:27] offset:16

; __device__ __forceinline__ unsigned cvt_pk_bf16(float lo, float hi) { unsigned r; asm volatile("v_cvt_pk_bf16_f32 %0, %1, %2" : "=v"(r) : "v"(lo), "v"(hi)); return r; }
; #define LAS __attribute__((address_space(3)))
; __device__ __forceinline__ void p0_out(const P0Desc& d, const LAS float* T, int wid, int lane) {
;     const int c8 = lane & 7;
; #pragma unroll
;     for (int j = 0; j < 4; ++j) { const int n = (lane >> 3) + 8 * j; const int sc = d.perm ? pg8::perm32(n) : n; const LAS float* sp = T + (8 * c8) * 257 + 32 * wid + sc;
;         u32x4 o; o.x = cvt_pk_bf16(sp[0 * 257], sp[1 * 257]); o.y = cvt_pk_bf16(sp[2 * 257], sp[3 * 257]); o.z = cvt_pk_bf16(sp[4 * 257], sp[5 * 257]); o.w = cvt_pk_bf16(sp[6 * 257], sp[7 * 257]);
;         *(u32x4*)(d.dst + (size_t)n * d.K + 8 * c8) = o; }
; }
; __global__ void __launch_bounds__(NTHR, 2) fwd_kernel(Args a) {
;     ...
;           while (have) {
;               p0_to_lds(dc, tv, T, wid, lane);
;               __syncthreads();
;               const bool hn = p0_decode(it + G, ts, wid, lane, dn); if (hn) p0_load(dn, tv);
;               p0_out(dc, T, wid, lane);
;               __syncthreads();
;               have = hn; it += G; dc = dn;
.LBB0_84:
	s_or_b64 exec, exec, s[36:37]
	s_cmp_eq_u64 s[26:27], 0
	s_cbranch_scc1 .Lp0_nogain_b
	global_load_dwordx4 v[248:251], v37, s[26:27]
	global_load_dwordx4 v[252:255], v37, s[26:27] offset:16
.Lp0_nogain_b:
.LBB0_85:
	v_cndmask_b32_e64 v46, v34, v43, s[18:19]
	v_lshl_add_u32 v46, v46, 2, v41
	ds_read_b32 v51, v46 offset:1028
	ds_read_b32 v52, v46
	v_cndmask_b32_e64 v55, v38, v47, s[18:19]
	v_lshl_add_u32 v58, v55, 2, v41
	v_mad_i64_i32 v[56:57], s[36:37], s51, v34, 0
	s_waitcnt lgkmcnt(0)
	v_cvt_pk_bf16_f32 v52, v52, v51
	ds_read_b32 v51, v46 offset:3084
	ds_read_b32 v53, v46 offset:2056
	v_lshl_add_u64 v[56:57], v[56:57], 1, s[20:21]
	v_lshl_add_u64 v[56:57], v[56:57], 0, v[36:37]
	s_add_i32 s55, s55, s82
	s_waitcnt lgkmcnt(0)
	v_cvt_pk_bf16_f32 v53, v53, v51
	ds_read_b32 v51, v46 offset:5140
	ds_read_b32 v54, v46 offset:4112
	s_and_b64 vcc, exec, s[6:7]
	s_mov_b32 s43, s56
	s_waitcnt lgkmcnt(0)
	v_cvt_pk_bf16_f32 v54, v54, v51
	ds_read_b32 v51, v46 offset:7196
	ds_read_b32 v46, v46 offset:6168
	s_waitcnt lgkmcnt(0)
	v_cvt_pk_bf16_f32 v55, v46, v51
	ds_read_b32 v46, v58 offset:1028
	ds_read_b32 v51, v58
	global_store_dwordx4 v[56:57], v[52:55], off
	v_mad_i64_i32 v[56:57], s[36:37], s51, v38, 0
	s_waitcnt lgkmcnt(0)
	v_cvt_pk_bf16_f32 v52, v51, v46
	ds_read_b32 v46, v58 offset:3084
	ds_read_b32 v51, v58 offset:2056
	s_waitcnt lgkmcnt(0)
	v_cvt_pk_bf16_f32 v53, v51, v46
	ds_read_b32 v46, v58 offset:5140
	ds_read_b32 v51, v58 offset:4112
	s_waitcnt lgkmcnt(0)
	v_cvt_pk_bf16_f32 v54, v51, v46
	ds_read_b32 v46, v58 offset:7196
	ds_read_b32 v51, v58 offset:6168
	v_cndmask_b32_e64 v55, v40, v48, s[18:19]
	v_lshl_add_u32 v58, v55, 2, v41
	s_waitcnt lgkmcnt(0)
	v_cvt_pk_bf16_f32 v55, v51, v46
	ds_read_b32 v46, v58 offset:1028
	ds_read_b32 v51, v58
	v_lshl_add_u64 v[56:57], v[56:57], 1, s[20:21]
	v_lshl_add_u64 v[56:57], v[56:57], 0, v[36:37]
	global_store_dwordx4 v[56:57], v[52:55], off
	s_waitcnt lgkmcnt(0)
	s_nop 0
	v_cvt_pk_bf16_f32 v52, v51, v46
	ds_read_b32 v46, v58 offset:3084
	ds_read_b32 v51, v58 offset:2056
	s_waitcnt lgkmcnt(0)
	v_cvt_pk_bf16_f32 v53, v51, v46
	ds_read_b32 v46, v58 offset:5140
	ds_read_b32 v51, v58 offset:4112
	s_waitcnt lgkmcnt(0)
	v_cvt_pk_bf16_f32 v54, v51, v46
	ds_read_b32 v46, v58 offset:7196
	ds_read_b32 v51, v58 offset:6168
	v_cndmask_b32_e64 v55, v42, v49, s[18:19]
	v_lshl_add_u32 v58, v55, 2, v41
	s_waitcnt lgkmcnt(0)
	v_cvt_pk_bf16_f32 v55, v51, v46
	ds_read_b32 v46, v58 offset:1028
	ds_read_b32 v51, v58
	v_mad_i64_i32 v[56:57], s[18:19], s51, v40, 0
	v_lshl_add_u64 v[56:57], v[56:57], 1, s[20:21]
	v_lshl_add_u64 v[56:57], v[56:57], 0, v[36:37]
	global_store_dwordx4 v[56:57], v[52:55], off
	v_mad_i64_i32 v[56:57], s[18:19], s51, v42, 0
	s_waitcnt lgkmcnt(0)
	v_cvt_pk_bf16_f32 v52, v51, v46
	ds_read_b32 v46, v58 offset:3084
	ds_read_b32 v51, v58 offset:2056
	s_waitcnt lgkmcnt(0)
	v_cvt_pk_bf16_f32 v53, v51, v46
	ds_read_b32 v46, v58 offset:5140
	ds_read_b32 v51, v58 offset:4112
	s_waitcnt lgkmcnt(0)
	v_cvt_pk_bf16_f32 v54, v51, v46
	ds_read_b32 v46, v58 offset:7196
	ds_read_b32 v51, v58 offset:6168
	v_lshl_add_u64 v[56:57], v[56:57], 1, s[20:21]
	s_mov_b64 s[18:19], s[28:29]
	s_mov_b32 s51, s42
	v_lshl_add_u64 v[56:57], v[56:57], 0, v[36:37]
	s_mov_b64 s[20:21], s[34:35]
	s_waitcnt lgkmcnt(0)
	v_cvt_pk_bf16_f32 v55, v51, v46
	global_store_dwordx4 v[56:57], v[52:55], off
	s_barrier
	s_cbranch_vccnz .LBB0_149
.LBB0_86:
	s_cmp_lg_u64 s[26:27], 0
	s_cselect_b64 s[36:37], -1, 0
	s_cmp_eq_u64 s[26:27], 0
	s_cbranch_scc1 .LBB0_144
	s_waitcnt vmcnt(0)
	v_mov_b32_e32 v56, v248
	v_mov_b32_e32 v57, v249
	v_pk_mul_f32 v[52:53], v[4:5], v[56:57] op_sel_hi:[1,0]
	v_pk_mul_f32 v[54:55], v[6:7], v[56:57] op_sel_hi:[1,0]
	v_mov_b32_e32 v46, v57
	ds_write_b128 v50, v[52:55]
	s_cbranch_execnz .LBB0_89

; #define LAS __attribute__((address_space(3)))
; __device__ __forceinline__ void p0_to_lds(const P0Desc& d, const f32x4 (&tv)[8], LAS float* T, int wid, int lane) {
; #pragma unroll
;     for (int i = 0; i < 8; ++i) { const float g = d.gk ? d.gk[i] : 1.f; LAS float* tp = T + (wid * 8 + i) * 257 + 4 * lane; tp[0] = tv[i].x * g; tp[1] = tv[i].y * g; tp[2] = tv[i].z * g; tp[3] = tv[i].w * g; }
; }
.LBB0_89:
	s_waitcnt vmcnt(0)
	v_pk_mul_f32 v[52:53], v[0:1], v[46:47] op_sel_hi:[1,0]
	v_add_u32_e32 v51, 0x404, v50
	ds_write2_b32 v51, v52, v53 offset1:1
	v_pk_mul_f32 v[52:53], v[2:3], v[46:47] op_sel_hi:[1,0]
	v_add_u32_e32 v46, 0x40c, v50
	ds_write2_b32 v46, v52, v53 offset1:1
	v_cndmask_b32_e64 v46, 0, 1, s[36:37]
	v_cmp_ne_u32_e64 s[6:7], 1, v46
	s_andn2_b64 vcc, exec, s[36:37]
	v_add_u32_e32 v51, 0x808, v50
	s_cbranch_vccnz .LBB0_145
	s_waitcnt vmcnt(0)
	v_mov_b32_e32 v52, v250
	v_mov_b32_e32 v53, v251
	v_pk_mul_f32 v[54:55], v[8:9], v[52:53] op_sel_hi:[1,0]
	v_pk_mul_f32 v[56:57], v[10:11], v[52:53] op_sel_hi:[1,0]
	v_mov_b32_e32 v46, v53
	ds_write2_b64 v51, v[54:55], v[56:57] offset1:1
	s_cbranch_execnz .LBB0_92

; #define LAS __attribute__((address_space(3)))
; __device__ __forceinline__ void p0_to_lds(const P0Desc& d, const f32x4 (&tv)[8], LAS float* T, int wid, int lane) {
; #pragma unroll
;     for (int i = 0; i < 8; ++i) { const float g = d.gk ? d.gk[i] : 1.f; LAS float* tp = T + (wid * 8 + i) * 257 + 4 * lane; tp[0] = tv[i].x * g; tp[1] = tv[i].y * g; tp[2] = tv[i].z * g; tp[3] = tv[i].w * g; }
; }
.LBB0_92:
	v_pk_mul_f32 v[52:53], v[12:13], v[46:47] op_sel_hi:[1,0]
	v_add_u32_e32 v51, 0xc0c, v50
	ds_write2_b32 v51, v52, v53 offset1:1
	v_pk_mul_f32 v[52:53], v[14:15], v[46:47] op_sel_hi:[1,0]
	v_add_u32_e32 v46, 0xc14, v50
	s_and_b64 vcc, exec, s[6:7]
	ds_write2_b32 v46, v52, v53 offset1:1
	s_cbranch_vccnz .LBB0_146
	s_waitcnt vmcnt(0)
	v_mov_b32_e32 v56, v252
	v_mov_b32_e32 v57, v253
	v_pk_mul_f32 v[52:53], v[16:17], v[56:57] op_sel_hi:[1,0]
	v_pk_mul_f32 v[54:55], v[18:19], v[56:57] op_sel_hi:[1,0]
	v_mov_b32_e32 v46, v57
	ds_write_b128 v50, v[52:55] offset:4112
	s_cbranch_execnz .LBB0_95

; #define LAS __attribute__((address_space(3)))
; __device__ __forceinline__ void p0_to_lds(const P0Desc& d, const f32x4 (&tv)[8], LAS float* T, int wid, int lane) {
; #pragma unroll
;     for (int i = 0; i < 8; ++i) { const float g = d.gk ? d.gk[i] : 1.f; LAS float* tp = T + (wid * 8 + i) * 257 + 4 * lane; tp[0] = tv[i].x * g; tp[1] = tv[i].y * g; tp[2] = tv[i].z * g; tp[3] = tv[i].w * g; }
; }
.LBB0_95:
	v_pk_mul_f32 v[52:53], v[20:21], v[46:47] op_sel_hi:[1,0]
	v_add_u32_e32 v51, 0x1414, v50
	ds_write2_b32 v51, v52, v53 offset1:1
	v_pk_mul_f32 v[52:53], v[22:23], v[46:47] op_sel_hi:[1,0]
	v_add_u32_e32 v46, 0x141c, v50
	s_and_b64 vcc, exec, s[6:7]
	v_add_u32_e32 v51, 0x1818, v50
	ds_write2_b32 v46, v52, v53 offset1:1
	s_cbranch_vccnz .LBB0_147
	s_waitcnt vmcnt(0)
	v_mov_b32_e32 v52, v254
	v_mov_b32_e32 v53, v255
	v_pk_mul_f32 v[54:55], v[28:29], v[52:53] op_sel_hi:[1,0]
	v_pk_mul_f32 v[56:57], v[30:31], v[52:53] op_sel_hi:[1,0]
	v_mov_b32_e32 v46, v53
	ds_write2_b64 v51, v[54:55], v[56:57] offset1:1
	s_cbranch_execnz .LBB0_98

; template <bool WITH_O> __device__ __forceinline__ void gla_sample(LAS unsigned char* lds, int uidx, const float* PRS, const float* GLRP, const float* w2, const float* gb, const float* gn, ...
;     ...
;     const size_t sb = ((size_t)(s * 4 + h) * DK) * DV + (tid & 63) * 4; f32x4 S[16];
; #pragma unroll
;     for (int kk = 0; kk < 16; ++kk) S[kk] = __builtin_nontemporal_load((const f32x4*)(s_in + sb + (size_t)(16 * wid + kk) * DV));
.LBB0_360:
	v_lshl_add_u64 v[0:1], s[24:25], 0, v[114:115]
	v_add_co_u32_e32 v2, vcc, 0x1000, v0
	global_load_dwordx4 v[60:63], v[0:1], off nt
	global_load_dwordx4 v[56:59], v[0:1], off offset:1024 nt
	global_load_dwordx4 v[52:55], v[0:1], off offset:2048 nt
	global_load_dwordx4 v[48:51], v[0:1], off offset:3072 nt
	v_addc_co_u32_e32 v3, vcc, 0, v1, vcc
	global_load_dwordx4 v[44:47], v[2:3], off nt
	global_load_dwordx4 v[40:43], v[2:3], off offset:1024 nt
	global_load_dwordx4 v[36:39], v[2:3], off offset:2048 nt
	global_load_dwordx4 v[32:35], v[2:3], off offset:3072 nt
	v_add_co_u32_e32 v2, vcc, s59, v0
	s_ashr_i32 s8, s55, 2
	s_nop 0
	v_addc_co_u32_e32 v3, vcc, 0, v1, vcc
	v_add_co_u32_e32 v0, vcc, 0x3000, v0
	global_load_dwordx4 v[28:31], v[2:3], off nt
	global_load_dwordx4 v[24:27], v[2:3], off offset:1024 nt
	global_load_dwordx4 v[20:23], v[2:3], off offset:2048 nt
	global_load_dwordx4 v[16:19], v[2:3], off offset:3072 nt
	v_addc_co_u32_e32 v1, vcc, 0, v1, vcc
	global_load_dwordx4 v[12:15], v[0:1], off nt
	global_load_dwordx4 v[8:11], v[0:1], off offset:1024 nt
	global_load_dwordx4 v[4:7], v[0:1], off offset:2048 nt
	s_nop 0
	global_load_dwordx4 v[0:3], v[0:1], off offset:3072 nt
	s_mul_hi_i32 s49, s8, 0x6400
	s_mul_i32 s48, s8, 0x6400
	s_and_saveexec_b64 s[6:7], s[42:43]
	s_xor_b64 s[6:7], exec, s[6:7]
	s_or_saveexec_b64 s[52:53], s[6:7]
	s_and_b32 s6, s55, 3
	s_add_i32 s34, s8, 0x2000
	v_mov_b64_e32 v[72:73], s[48:49]
	s_xor_b64 exec, exec, s[52:53]
	s_cbranch_execz .LBB0_362
; __device__ __forceinline__ float logsig_f(float z) { return fminf(z, 0.f) - __logf(1.f + __expf(-fabsf(z))); }
; #pragma unroll
;     for (int sp = 0; sp < NSP1; ++sp) v += PRS[((size_t)sp * NS + s) * PRSW + col];
;     return v; }
; template <bool WITH_O> __device__ __forceinline__ void gla_sample(LAS unsigned char* lds, int uidx, const float* PRS, const float* GLRP, const float* w2, const float* gb, const float* gn, ...
;     ...
;     if (tid < DK) { const int col = h * DK + tid; float z = gb[col];
; #pragma unroll
;         for (int rr = 0; rr < RANK; ++rr) { float g = 0.f;
; #pragma unroll
;             for (int sp = 0; sp < NSP1; ++sp) g += GLRP[((size_t)sp * MPAD + row) * RANK + rr];
;             z += g * w2[rr * QKD + col]; }
;         smA[tid] = __expf(logsig_f(z) * (1.f / 16.f)); smK[tid] = prs_sum(PRS, s, 3584 + col); if (WITH_O) smQ[tid] = prs_sum(PRS, s, 3072 + col) * 0.08838834764831845f; }
;     const int dv4 = (tid & 63) * 4; const f32x4 v = prs_sum4(PRS, s, 4096 + h * DV + dv4);
	s_ashr_i32 s35, s34, 31
	v_lshl_add_u32 v64, s6, 7, v112
	s_lshl_b64 s[46:47], s[34:35], 6
	v_lshlrev_b32_e32 v64, 2, v64
	s_add_u32 s46, s30, s46
	s_addc_u32 s47, s31, s47
	global_load_dword v65, v64, s[38:39]
	global_load_dwordx4 v[66:69], v169, s[46:47]
	global_load_dwordx4 v[74:77], v169, s[46:47] offset:16
	global_load_dwordx4 v[78:81], v169, s[46:47] offset:32
	global_load_dwordx4 v[82:85], v169, s[46:47] offset:48
	s_add_u32 s56, s46, 0x84000
	s_addc_u32 s57, s47, 0
	global_load_dwordx4 v[86:89], v169, s[56:57]
	global_load_dwordx4 v[90:93], v169, s[56:57] offset:16
	global_load_dwordx4 v[94:97], v169, s[56:57] offset:32
	global_load_dwordx4 v[98:101], v169, s[56:57] offset:48
	s_add_u32 s56, s46, 0x108000
	s_addc_u32 s57, s47, 0
	global_load_dwordx4 v[102:105], v169, s[56:57]
	global_load_dwordx4 v[106:109], v169, s[56:57] offset:16
	global_load_dwordx4 v[116:119], v169, s[56:57] offset:32
	global_load_dwordx4 v[126:129], v169, s[56:57] offset:48
	s_add_u32 s56, s46, 0x18c000
	s_addc_u32 s57, s47, 0
	global_load_dwordx4 v[130:133], v169, s[56:57]
	global_load_dwordx4 v[134:137], v169, s[56:57] offset:16
	global_load_dwordx4 v[138:141], v169, s[56:57] offset:32
	global_load_dwordx4 v[142:145], v169, s[56:57] offset:48
	global_load_dword v70, v64, s[4:5]
	global_load_dword v71, v64, s[4:5] offset:2048
	s_add_u32 s56, s4, 0x1000
	s_addc_u32 s57, s5, 0
	global_load_dword v110, v64, s[56:57]
	global_load_dword v111, v64, s[56:57] offset:2048
	s_add_u32 s56, s4, 0x2000
	s_addc_u32 s57, s5, 0
	global_load_dword v125, v64, s[56:57]
	global_load_dword v146, v64, s[56:57] offset:2048
	s_add_u32 s56, s4, 0x3000
	s_addc_u32 s57, s5, 0
	global_load_dword v147, v64, s[56:57]
	global_load_dword v148, v64, s[56:57] offset:2048
	s_add_u32 s56, s4, 0x4000
	s_addc_u32 s57, s5, 0
	global_load_dword v149, v64, s[56:57]
	global_load_dword v150, v64, s[56:57] offset:2048
	s_add_u32 s56, s4, 0x5000
	s_addc_u32 s57, s5, 0
	global_load_dword v151, v64, s[56:57]
	global_load_dword v152, v64, s[56:57] offset:2048
	s_add_u32 s56, s4, 0x6000
	s_addc_u32 s57, s5, 0
	global_load_dword v153, v64, s[56:57]
	global_load_dword v154, v64, s[56:57] offset:2048
	s_add_u32 s56, s4, 0x7000
	s_addc_u32 s57, s5, 0
	global_load_dword v155, v64, s[56:57]
	global_load_dword v156, v64, s[56:57] offset:2048
	s_mul_i32 s98, s8, 0x6400
	s_add_u32 s98, s22, s98
	s_addc_u32 s99, s23, 0
	s_add_u32 s98, s98, 0x3000
	s_addc_u32 s99, s99, 0
	global_load_dword v157, v64, s[98:99] offset:2048
	global_load_dword v161, v64, s[98:99]
	s_add_u32 s56, s98, 0x320000
	s_addc_u32 s57, s99, 0
	global_load_dword v158, v64, s[56:57] offset:2048
	global_load_dword v162, v64, s[56:57]
	s_add_u32 s56, s98, 0x640000
	s_addc_u32 s57, s99, 0
	global_load_dword v159, v64, s[56:57] offset:2048
	global_load_dword v163, v64, s[56:57]
	s_add_u32 s56, s98, 0x960000
	s_addc_u32 s57, s99, 0
	global_load_dword v160, v64, s[56:57] offset:2048
	global_load_dword v164, v64, s[56:57]
	s_waitcnt vmcnt(0)
	v_add_f32_e32 v165, 0, v66
	v_add_f32_e32 v165, v165, v86
	v_add_f32_e32 v165, v165, v102
	v_add_f32_e32 v165, v165, v130
	v_fmac_f32_e32 v65, v165, v70
	v_add_f32_e32 v165, 0, v67
	v_add_f32_e32 v165, v165, v87
	v_add_f32_e32 v165, v165, v103
	v_add_f32_e32 v165, v165, v131
	v_fmac_f32_e32 v65, v165, v71
	v_add_f32_e32 v165, 0, v68
	v_add_f32_e32 v165, v165, v88
	v_add_f32_e32 v165, v165, v104
	v_add_f32_e32 v165, v165, v132
	v_fmac_f32_e32 v65, v165, v110
	v_add_f32_e32 v165, 0, v69
	v_add_f32_e32 v165, v165, v89
	v_add_f32_e32 v165, v165, v105
	v_add_f32_e32 v165, v165, v133
	v_fmac_f32_e32 v65, v165, v111
	v_add_f32_e32 v165, 0, v74
	v_add_f32_e32 v165, v165, v90
	v_add_f32_e32 v165, v165, v106
	v_add_f32_e32 v165, v165, v134
	v_fmac_f32_e32 v65, v165, v125
	v_add_f32_e32 v165, 0, v75
	v_add_f32_e32 v165, v165, v91
	v_add_f32_e32 v165, v165, v107
	v_add_f32_e32 v165, v165, v135
	v_fmac_f32_e32 v65, v165, v146
	v_add_f32_e32 v165, 0, v76
	v_add_f32_e32 v165, v165, v92
	v_add_f32_e32 v165, v165, v108
	v_add_f32_e32 v165, v165, v136
	v_fmac_f32_e32 v65, v165, v147
	v_add_f32_e32 v165, 0, v77
	v_add_f32_e32 v165, v165, v93
	v_add_f32_e32 v165, v165, v109
	v_add_f32_e32 v165, v165, v137
	v_fmac_f32_e32 v65, v165, v148
	v_add_f32_e32 v165, 0, v78
	v_add_f32_e32 v165, v165, v94
	v_add_f32_e32 v165, v165, v116
	v_add_f32_e32 v165, v165, v138
	v_fmac_f32_e32 v65, v165, v149
	v_add_f32_e32 v165, 0, v79
	v_add_f32_e32 v165, v165, v95
	v_add_f32_e32 v165, v165, v117
	v_add_f32_e32 v165, v165, v139
	v_fmac_f32_e32 v65, v165, v150
	v_add_f32_e32 v165, 0, v80
	v_add_f32_e32 v165, v165, v96
	v_add_f32_e32 v165, v165, v118
	v_add_f32_e32 v165, v165, v140
	v_fmac_f32_e32 v65, v165, v151
	v_add_f32_e32 v165, 0, v81
	v_add_f32_e32 v165, v165, v97
	v_add_f32_e32 v165, v165, v119
	v_add_f32_e32 v165, v165, v141
	v_fmac_f32_e32 v65, v165, v152
	v_add_f32_e32 v165, 0, v82
	v_add_f32_e32 v165, v165, v98
	v_add_f32_e32 v165, v165, v126
	v_add_f32_e32 v165, v165, v142
	v_fmac_f32_e32 v65, v165, v153
	v_add_f32_e32 v165, 0, v83
	v_add_f32_e32 v165, v165, v99
	v_add_f32_e32 v165, v165, v127
	v_add_f32_e32 v165, v165, v143
	v_fmac_f32_e32 v65, v165, v154
	v_add_f32_e32 v165, 0, v84
	v_add_f32_e32 v165, v165, v100
	v_add_f32_e32 v165, v165, v128
	v_add_f32_e32 v165, v165, v144
	v_fmac_f32_e32 v65, v165, v155
	v_add_f32_e32 v165, 0, v85
	v_add_f32_e32 v165, v165, v101
	v_add_f32_e32 v165, v165, v129
	v_add_f32_e32 v165, v165, v145
	v_fmac_f32_e32 v65, v165, v156
	v_mul_f32_e64 v166, |v65|, s17
	v_exp_f32_e32 v166, v166
	v_min_f32_e32 v167, 0, v65
	v_add_f32_e32 v166, 1.0, v166
	v_cmp_gt_f32_e32 vcc, s14, v166
	s_nop 1
	v_cndmask_b32_e64 v168, 0, 32, vcc
	v_ldexp_f32 v166, v166, v168
	v_log_f32_e32 v166, v166
	s_nop 0
	v_mul_f32_e32 v168, 0x3f317217, v166
	v_fma_f32 v168, v166, s18, -v168
	v_fmac_f32_e32 v168, 0x3377d1cf, v166
	v_fmac_f32_e32 v168, 0x3f317217, v166
	v_cmp_lt_f32_e64 s[46:47], |v166|, s19
	s_nop 1
	v_cndmask_b32_e64 v166, v166, v168, s[46:47]
	v_cndmask_b32_e32 v168, 0, v218, vcc
	v_sub_f32_e32 v166, v166, v168
	v_sub_f32_e32 v167, v167, v166
	v_mul_f32_e32 v167, 0x3d800000, v167
	v_mul_f32_e32 v167, 0x3fb8aa3b, v167
	v_exp_f32_e32 v178, v167
	v_add_f32_e32 v166, 0, v157
	v_add_f32_e32 v166, v166, v158
	v_add_f32_e32 v166, v166, v159
	v_add_f32_e32 v166, v166, v160
	v_add_f32_e32 v167, 0, v161
	v_add_f32_e32 v167, v167, v162
	v_add_f32_e32 v167, v167, v163
	v_add_f32_e32 v167, v167, v164
	v_mul_f32_e32 v167, 0x3db504f3, v167
	ds_write2st64_b32 v122, v178, v166 offset1:2
	ds_write_b32 v122, v167 offset:1024

; __device__ __forceinline__ unsigned cvt_pk_bf16(float lo, float hi) { unsigned r; asm volatile("v_cvt_pk_bf16_f32 %0, %1, %2" : "=v"(r) : "v"(lo), "v"(hi)); return r; }
; #define EPI_ST(p, v) __builtin_nontemporal_store((v), (p))
; __device__ __forceinline__ float bf_lo(unsigned w) { return __uint_as_float(w << 16); }
; __device__ __forceinline__ float bf_hi(unsigned w) { return __uint_as_float(w & 0xffff0000u); }
;     __device__ __forceinline__ void operator()(const f32x4 (&acc)[2][2][4][2], const pg8::Unit& u, int wr, int wc, int fr, int fq) const {
;     ...
; #pragma unroll
;         for (int ai = 0; ai < 2; ++ai)
; #pragma unroll
;             for (int m = 0; m < 4; ++m) { const int row = row0 + ai * 128 + m * 16;
;                 { bf16_t* xb = XB + (size_t)row * DM + col0; float ss = 0.f;
; #pragma unroll
;                     for (int bj = 0; bj < 2; ++bj) { f32x4 b0, b1;
;                         if (baseP) { const float* bp = baseP + (size_t)row * DM + col0 + bj * 128; b0 = *(const f32x4*)bp; b1 = *(const f32x4*)(bp + 4); }
;                         else { const u32x4 bw = *(const u32x4*)(xb + bj * 128); b0 = (f32x4){bf_lo(bw.x), bf_hi(bw.x), bf_lo(bw.y), bf_hi(bw.y)}; b1 = (f32x4){bf_lo(bw.z), bf_hi(bw.z), bf_lo(bw.w), bf_hi(bw.w)}; }
;                         const f32x4 v0 = b0 + acc[ai][bj][m][0], v1 = b1 + acc[ai][bj][m][1];
;                         ss += ((v0.x * v0.x + v0.y * v0.y) + (v0.z * v0.z + v0.w * v0.w)) + ((v1.x * v1.x + v1.y * v1.y) + (v1.z * v1.z + v1.w * v1.w));
;                         u32x4 w; w.x = cvt_pk_bf16(v0.x, v0.y); w.y = cvt_pk_bf16(v0.z, v0.w); w.z = cvt_pk_bf16(v1.x, v1.y); w.w = cvt_pk_bf16(v1.z, v1.w); EPI_ST((u32x4*)(xb + bj * 128), w); }
;                     if (SS) { ss += __shfl_xor(ss, 16); ss += __shfl_xor(ss, 32); if (fq == 0) SS[(size_t)row * 32 + u.pn * 4 + wc] = ss; } }
;                 asm volatile("" ::: "memory"); }
.LBB0_563:
	s_mov_b32 s5, s58
	v_mov_b32_e32 v160, v163
	s_mov_b32 s56, s69
	v_mov_b32_e32 v144, v162
	s_lshl_b32 s54, s5, 6
	s_lshl_b32 s5, s22, 8
	s_lshl_b32 s6, s56, 5
	s_add_i32 s6, s6, s5
	v_lshl_add_u32 v142, v160, 3, s6
	v_readlane_b32 s78, v244, 5
	s_cmp_gt_i32 s4, -1
	v_ashrrev_i32_e32 v143, 31, v142
	s_mov_b64 s[6:7], -1
	v_readlane_b32 s79, v244, 6
	s_cbranch_scc1 .LBB0_566
	s_lshl_b32 s5, s40, 8
	s_add_i32 s5, s54, s5
	v_add_u32_e32 v146, s5, v144
	v_lshlrev_b32_e32 v247, 12, v146
	v_lshl_add_u32 v247, v142, 1, v247
	v_lshlrev_b32_e32 v255, 7, v146
	v_xor_b32_e32 v166, 16, v211
	v_xor_b32_e32 v167, 32, v211
	v_lshlrev_b32_e32 v166, 2, v166
	v_lshlrev_b32_e32 v167, 2, v167
	s_lshl_b32 s5, s22, 4
	s_lshl_b32 s30, s56, 2
	s_add_i32 s5, s5, s30
	s_add_u32 s100, s28, s5
	s_addc_u32 s101, s29, 0
	s_and_b64 vcc, exec, s[38:39]
	s_cbranch_vccz .Lres1_bf16
	v_lshlrev_b32_e32 v248, 1, v247
	global_load_dwordx4 v[128:131], v248, s[2:3]
	global_load_dwordx4 v[132:135], v248, s[2:3] offset:16
	global_load_dwordx4 v[142:145], v248, s[2:3] offset:512
	global_load_dwordx4 v[146:149], v248, s[2:3] offset:528
	s_add_u32 s98, s2, 0x20000
	s_addc_u32 s99, s3, 0
	global_load_dwordx4 v[150:153], v248, s[98:99]
	global_load_dwordx4 v[154:157], v248, s[98:99] offset:16
	global_load_dwordx4 v[158:161], v248, s[98:99] offset:512
	global_load_dwordx4 v[178:181], v248, s[98:99] offset:528
	s_add_u32 s98, s2, 0x40000
	s_addc_u32 s99, s3, 0
	global_load_dwordx4 v[182:185], v248, s[98:99]
	global_load_dwordx4 v[186:189], v248, s[98:99] offset:16
	global_load_dwordx4 v[190:193], v248, s[98:99] offset:512
	global_load_dwordx4 v[194:197], v248, s[98:99] offset:528
	s_add_u32 s98, s2, 0x60000
	s_addc_u32 s99, s3, 0
	global_load_dwordx4 v[198:201], v248, s[98:99]
	global_load_dwordx4 v[202:205], v248, s[98:99] offset:16
	global_load_dwordx4 v[206:209], v248, s[98:99] offset:512
	global_load_dwordx4 v[226:229], v248, s[98:99] offset:528
	s_waitcnt vmcnt(12)
	v_pk_add_f32 v[68:69], v[68:69], v[128:129]
	v_pk_add_f32 v[70:71], v[70:71], v[130:131]
	v_pk_add_f32 v[64:65], v[64:65], v[132:133]
	v_pk_add_f32 v[66:67], v[66:67], v[134:135]
	v_pk_add_f32 v[48:49], v[48:49], v[142:143]
	v_pk_add_f32 v[50:51], v[50:51], v[144:145]
	v_pk_add_f32 v[44:45], v[44:45], v[146:147]
	v_pk_add_f32 v[46:47], v[46:47], v[148:149]
	v_mul_f32_e32 v250, v69, v69
	v_mul_f32_e32 v252, v71, v71
	v_fmac_f32_e32 v250, v68, v68
	v_fmac_f32_e32 v252, v70, v70
	v_mul_f32_e32 v253, v65, v65
	v_mul_f32_e32 v254, v67, v67
	v_add_f32_e32 v250, v250, v252
	v_fmac_f32_e32 v253, v64, v64
	v_fmac_f32_e32 v254, v66, v66
	v_add_f32_e32 v253, v253, v254
	v_add_f32_e32 v250, v250, v253
	v_mul_f32_e32 v251, v49, v49
	v_mul_f32_e32 v252, v51, v51
	v_fmac_f32_e32 v251, v48, v48
	v_fmac_f32_e32 v252, v50, v50
	v_mul_f32_e32 v253, v45, v45
	v_mul_f32_e32 v254, v47, v47
	v_add_f32_e32 v251, v251, v252
	v_fmac_f32_e32 v253, v44, v44
	v_fmac_f32_e32 v254, v46, v46
	v_add_f32_e32 v253, v253, v254
	v_add_f32_e32 v251, v251, v253
	v_cvt_pk_bf16_f32 v128, v68, v69
	v_cvt_pk_bf16_f32 v129, v70, v71
	v_cvt_pk_bf16_f32 v130, v64, v65
	v_cvt_pk_bf16_f32 v131, v66, v67
	v_cvt_pk_bf16_f32 v142, v48, v49
	v_cvt_pk_bf16_f32 v143, v50, v51
	v_cvt_pk_bf16_f32 v144, v44, v45
	v_cvt_pk_bf16_f32 v145, v46, v47
	v_add_f32_e32 v132, v250, v251
	global_store_dwordx4 v247, v[128:131], s[26:27]
	global_store_dwordx4 v247, v[142:145], s[26:27] offset:256
	s_add_u32 s98, s2, 0x100000
	s_addc_u32 s99, s3, 0
	global_load_dwordx4 v[68:71], v248, s[98:99]
	global_load_dwordx4 v[64:67], v248, s[98:99] offset:16
	global_load_dwordx4 v[48:51], v248, s[98:99] offset:512
	global_load_dwordx4 v[44:47], v248, s[98:99] offset:528
	s_waitcnt vmcnt(14)
	v_pk_add_f32 v[60:61], v[60:61], v[150:151]
	v_pk_add_f32 v[62:63], v[62:63], v[152:153]
	v_pk_add_f32 v[56:57], v[56:57], v[154:155]
	v_pk_add_f32 v[58:59], v[58:59], v[156:157]
	v_pk_add_f32 v[28:29], v[28:29], v[158:159]
	v_pk_add_f32 v[30:31], v[30:31], v[160:161]
	v_pk_add_f32 v[24:25], v[24:25], v[178:179]
	v_pk_add_f32 v[26:27], v[26:27], v[180:181]
	v_mul_f32_e32 v250, v61, v61
	v_mul_f32_e32 v252, v63, v63
	v_fmac_f32_e32 v250, v60, v60
	v_fmac_f32_e32 v252, v62, v62
	v_mul_f32_e32 v253, v57, v57
	v_mul_f32_e32 v254, v59, v59
	v_add_f32_e32 v250, v250, v252
	v_fmac_f32_e32 v253, v56, v56
	v_fmac_f32_e32 v254, v58, v58
	v_add_f32_e32 v253, v253, v254
	v_add_f32_e32 v250, v250, v253
	v_mul_f32_e32 v251, v29, v29
	v_mul_f32_e32 v252, v31, v31
	v_fmac_f32_e32 v251, v28, v28
	v_fmac_f32_e32 v252, v30, v30
	v_mul_f32_e32 v253, v25, v25
	v_mul_f32_e32 v254, v27, v27
	v_add_f32_e32 v251, v251, v252
	v_fmac_f32_e32 v253, v24, v24
	v_fmac_f32_e32 v254, v26, v26
	v_add_f32_e32 v253, v253, v254
	v_add_f32_e32 v251, v251, v253
	v_cvt_pk_bf16_f32 v150, v60, v61
	v_cvt_pk_bf16_f32 v151, v62, v63
	v_cvt_pk_bf16_f32 v152, v56, v57
	v_cvt_pk_bf16_f32 v153, v58, v59
	v_cvt_pk_bf16_f32 v158, v28, v29
	v_cvt_pk_bf16_f32 v159, v30, v31
	v_cvt_pk_bf16_f32 v160, v24, v25
	v_cvt_pk_bf16_f32 v161, v26, v27
	v_add_f32_e32 v154, v250, v251
	s_add_u32 s98, s26, 0x10000
	s_addc_u32 s99, s27, 0
	global_store_dwordx4 v247, v[150:153], s[98:99]
	global_store_dwordx4 v247, v[158:161], s[98:99] offset:256
	s_add_u32 s98, s2, 0x120000
	s_addc_u32 s99, s3, 0
	global_load_dwordx4 v[60:63], v248, s[98:99]
	global_load_dwordx4 v[56:59], v248, s[98:99] offset:16
	global_load_dwordx4 v[28:31], v248, s[98:99] offset:512
	global_load_dwordx4 v[24:27], v248, s[98:99] offset:528
	s_waitcnt vmcnt(16)
; __device__ __forceinline__ unsigned cvt_pk_bf16(float lo, float hi) { unsigned r; asm volatile("v_cvt_pk_bf16_f32 %0, %1, %2" : "=v"(r) : "v"(lo), "v"(hi)); return r; }
; #define EPI_ST(p, v) __builtin_nontemporal_store((v), (p))
; __device__ __forceinline__ float bf_lo(unsigned w) { return __uint_as_float(w << 16); }
; __device__ __forceinline__ float bf_hi(unsigned w) { return __uint_as_float(w & 0xffff0000u); }
;     __device__ __forceinline__ void operator()(const f32x4 (&acc)[2][2][4][2], const pg8::Unit& u, int wr, int wc, int fr, int fq) const {
;     ...
;         for (int ai = 0; ai < 2; ++ai)
; #pragma unroll
;             for (int m = 0; m < 4; ++m) { const int row = row0 + ai * 128 + m * 16;
;                 { bf16_t* xb = XB + (size_t)row * DM + col0; float ss = 0.f;
; #pragma unroll
;                     for (int bj = 0; bj < 2; ++bj) { f32x4 b0, b1;
;                         if (baseP) { const float* bp = baseP + (size_t)row * DM + col0 + bj * 128; b0 = *(const f32x4*)bp; b1 = *(const f32x4*)(bp + 4); }
;                         else { const u32x4 bw = *(const u32x4*)(xb + bj * 128); b0 = (f32x4){bf_lo(bw.x), bf_hi(bw.x), bf_lo(bw.y), bf_hi(bw.y)}; b1 = (f32x4){bf_lo(bw.z), bf_hi(bw.z), bf_lo(bw.w), bf_hi(bw.w)}; }
;                         const f32x4 v0 = b0 + acc[ai][bj][m][0], v1 = b1 + acc[ai][bj][m][1];
;                         ss += ((v0.x * v0.x + v0.y * v0.y) + (v0.z * v0.z + v0.w * v0.w)) + ((v1.x * v1.x + v1.y * v1.y) + (v1.z * v1.z + v1.w * v1.w));
;                         u32x4 w; w.x = cvt_pk_bf16(v0.x, v0.y); w.y = cvt_pk_bf16(v0.z, v0.w); w.z = cvt_pk_bf16(v1.x, v1.y); w.w = cvt_pk_bf16(v1.z, v1.w); EPI_ST((u32x4*)(xb + bj * 128), w); }
;                     if (SS) { ss += __shfl_xor(ss, 16); ss += __shfl_xor(ss, 32); if (fq == 0) SS[(size_t)row * 32 + u.pn * 4 + wc] = ss; } }
;                 asm volatile("" ::: "memory"); }
	v_pk_add_f32 v[40:41], v[40:41], v[182:183]
	v_pk_add_f32 v[42:43], v[42:43], v[184:185]
	v_pk_add_f32 v[32:33], v[32:33], v[186:187]
	v_pk_add_f32 v[34:35], v[34:35], v[188:189]
	v_pk_add_f32 v[12:13], v[12:13], v[190:191]
	v_pk_add_f32 v[14:15], v[14:15], v[192:193]
	v_pk_add_f32 v[8:9], v[8:9], v[194:195]
	v_pk_add_f32 v[10:11], v[10:11], v[196:197]
	v_mul_f32_e32 v250, v41, v41
	v_mul_f32_e32 v252, v43, v43
	v_fmac_f32_e32 v250, v40, v40
	v_fmac_f32_e32 v252, v42, v42
	v_mul_f32_e32 v253, v33, v33
	v_mul_f32_e32 v254, v35, v35
	v_add_f32_e32 v250, v250, v252
	v_fmac_f32_e32 v253, v32, v32
	v_fmac_f32_e32 v254, v34, v34
	v_add_f32_e32 v253, v253, v254
	v_add_f32_e32 v250, v250, v253
	v_mul_f32_e32 v251, v13, v13
	v_mul_f32_e32 v252, v15, v15
	v_fmac_f32_e32 v251, v12, v12
	v_fmac_f32_e32 v252, v14, v14
	v_mul_f32_e32 v253, v9, v9
	v_mul_f32_e32 v254, v11, v11
	v_add_f32_e32 v251, v251, v252
	v_fmac_f32_e32 v253, v8, v8
	v_fmac_f32_e32 v254, v10, v10
	v_add_f32_e32 v253, v253, v254
	v_add_f32_e32 v251, v251, v253
	v_cvt_pk_bf16_f32 v182, v40, v41
	v_cvt_pk_bf16_f32 v183, v42, v43
	v_cvt_pk_bf16_f32 v184, v32, v33
	v_cvt_pk_bf16_f32 v185, v34, v35
	v_cvt_pk_bf16_f32 v190, v12, v13
	v_cvt_pk_bf16_f32 v191, v14, v15
	v_cvt_pk_bf16_f32 v192, v8, v9
	v_cvt_pk_bf16_f32 v193, v10, v11
	v_add_f32_e32 v186, v250, v251
	s_add_u32 s98, s26, 0x20000
	s_addc_u32 s99, s27, 0
	global_store_dwordx4 v247, v[182:185], s[98:99]
	global_store_dwordx4 v247, v[190:193], s[98:99] offset:256
	s_add_u32 s98, s2, 0x140000
	s_addc_u32 s99, s3, 0
	global_load_dwordx4 v[40:43], v248, s[98:99]
	global_load_dwordx4 v[32:35], v248, s[98:99] offset:16
	global_load_dwordx4 v[12:15], v248, s[98:99] offset:512
	global_load_dwordx4 v[8:11], v248, s[98:99] offset:528
	s_waitcnt vmcnt(18)
	v_pk_add_f32 v[20:21], v[20:21], v[198:199]
	v_pk_add_f32 v[22:23], v[22:23], v[200:201]
	v_pk_add_f32 v[16:17], v[16:17], v[202:203]
	v_pk_add_f32 v[18:19], v[18:19], v[204:205]
	v_pk_add_f32 v[4:5], v[4:5], v[206:207]
	v_pk_add_f32 v[6:7], v[6:7], v[208:209]
	v_pk_add_f32 v[0:1], v[0:1], v[226:227]
	v_pk_add_f32 v[2:3], v[2:3], v[228:229]
	v_mul_f32_e32 v250, v21, v21
	v_mul_f32_e32 v252, v23, v23
	v_fmac_f32_e32 v250, v20, v20
	v_fmac_f32_e32 v252, v22, v22
	v_mul_f32_e32 v253, v17, v17
	v_mul_f32_e32 v254, v19, v19
	v_add_f32_e32 v250, v250, v252
	v_fmac_f32_e32 v253, v16, v16
	v_fmac_f32_e32 v254, v18, v18
	v_add_f32_e32 v253, v253, v254
	v_add_f32_e32 v250, v250, v253
	v_mul_f32_e32 v251, v5, v5
	v_mul_f32_e32 v252, v7, v7
	v_fmac_f32_e32 v251, v4, v4
	v_fmac_f32_e32 v252, v6, v6
	v_mul_f32_e32 v253, v1, v1
	v_mul_f32_e32 v254, v3, v3
	v_add_f32_e32 v251, v251, v252
	v_fmac_f32_e32 v253, v0, v0
	v_fmac_f32_e32 v254, v2, v2
	v_add_f32_e32 v253, v253, v254
	v_add_f32_e32 v251, v251, v253
	v_cvt_pk_bf16_f32 v198, v20, v21
	v_cvt_pk_bf16_f32 v199, v22, v23
	v_cvt_pk_bf16_f32 v200, v16, v17
	v_cvt_pk_bf16_f32 v201, v18, v19
	v_cvt_pk_bf16_f32 v206, v4, v5
	v_cvt_pk_bf16_f32 v207, v6, v7
	v_cvt_pk_bf16_f32 v208, v0, v1
	v_cvt_pk_bf16_f32 v209, v2, v3
	v_add_f32_e32 v202, v250, v251
	s_add_u32 s98, s26, 0x30000
	s_addc_u32 s99, s27, 0
	global_store_dwordx4 v247, v[198:201], s[98:99]
	global_store_dwordx4 v247, v[206:209], s[98:99] offset:256
	s_add_u32 s98, s2, 0x160000
	s_addc_u32 s99, s3, 0
	global_load_dwordx4 v[20:23], v248, s[98:99]
	global_load_dwordx4 v[16:19], v248, s[98:99] offset:16
	global_load_dwordx4 v[4:7], v248, s[98:99] offset:512
	global_load_dwordx4 v[0:3], v248, s[98:99] offset:528
	s_waitcnt vmcnt(18)
	v_pk_add_f32 v[124:125], v[124:125], v[68:69]
	v_pk_add_f32 v[126:127], v[126:127], v[70:71]
	v_pk_add_f32 v[120:121], v[120:121], v[64:65]
	v_pk_add_f32 v[122:123], v[122:123], v[66:67]
	v_pk_add_f32 v[116:117], v[116:117], v[48:49]
	v_pk_add_f32 v[118:119], v[118:119], v[50:51]
	v_pk_add_f32 v[112:113], v[112:113], v[44:45]
	v_pk_add_f32 v[114:115], v[114:115], v[46:47]
	v_mul_f32_e32 v250, v125, v125
	v_mul_f32_e32 v252, v127, v127
	v_fmac_f32_e32 v250, v124, v124
	v_fmac_f32_e32 v252, v126, v126
	v_mul_f32_e32 v253, v121, v121
	v_mul_f32_e32 v254, v123, v123
	v_add_f32_e32 v250, v250, v252
	v_fmac_f32_e32 v253, v120, v120
	v_fmac_f32_e32 v254, v122, v122
	v_add_f32_e32 v253, v253, v254
	v_add_f32_e32 v250, v250, v253
	v_mul_f32_e32 v251, v117, v117
	v_mul_f32_e32 v252, v119, v119
	v_fmac_f32_e32 v251, v116, v116
	v_fmac_f32_e32 v252, v118, v118
	v_mul_f32_e32 v253, v113, v113
	v_mul_f32_e32 v254, v115, v115
	v_add_f32_e32 v251, v251, v252
	v_fmac_f32_e32 v253, v112, v112
	v_fmac_f32_e32 v254, v114, v114
	v_add_f32_e32 v253, v253, v254
	v_add_f32_e32 v251, v251, v253
	v_cvt_pk_bf16_f32 v68, v124, v125
	v_cvt_pk_bf16_f32 v69, v126, v127
	v_cvt_pk_bf16_f32 v70, v120, v121
	v_cvt_pk_bf16_f32 v71, v122, v123
	v_cvt_pk_bf16_f32 v48, v116, v117
	v_cvt_pk_bf16_f32 v49, v118, v119
	v_cvt_pk_bf16_f32 v50, v112, v113
	v_cvt_pk_bf16_f32 v51, v114, v115
	v_add_f32_e32 v64, v250, v251
	s_add_u32 s98, s26, 0x80000
	s_addc_u32 s99, s27, 0
	global_store_dwordx4 v247, v[68:71], s[98:99]
	global_store_dwordx4 v247, v[48:51], s[98:99] offset:256
	s_waitcnt vmcnt(14)
; __device__ __forceinline__ unsigned cvt_pk_bf16(float lo, float hi) { unsigned r; asm volatile("v_cvt_pk_bf16_f32 %0, %1, %2" : "=v"(r) : "v"(lo), "v"(hi)); return r; }
; #define EPI_ST(p, v) __builtin_nontemporal_store((v), (p))
; __device__ __forceinline__ float bf_lo(unsigned w) { return __uint_as_float(w << 16); }
; __device__ __forceinline__ float bf_hi(unsigned w) { return __uint_as_float(w & 0xffff0000u); }
;     __device__ __forceinline__ void operator()(const f32x4 (&acc)[2][2][4][2], const pg8::Unit& u, int wr, int wc, int fr, int fq) const {
;     ...
;         for (int ai = 0; ai < 2; ++ai)
; #pragma unroll
;             for (int m = 0; m < 4; ++m) { const int row = row0 + ai * 128 + m * 16;
;                 { bf16_t* xb = XB + (size_t)row * DM + col0; float ss = 0.f;
; #pragma unroll
;                     for (int bj = 0; bj < 2; ++bj) { f32x4 b0, b1;
;                         if (baseP) { const float* bp = baseP + (size_t)row * DM + col0 + bj * 128; b0 = *(const f32x4*)bp; b1 = *(const f32x4*)(bp + 4); }
;                         else { const u32x4 bw = *(const u32x4*)(xb + bj * 128); b0 = (f32x4){bf_lo(bw.x), bf_hi(bw.x), bf_lo(bw.y), bf_hi(bw.y)}; b1 = (f32x4){bf_lo(bw.z), bf_hi(bw.z), bf_lo(bw.w), bf_hi(bw.w)}; }
;                         const f32x4 v0 = b0 + acc[ai][bj][m][0], v1 = b1 + acc[ai][bj][m][1];
;                         ss += ((v0.x * v0.x + v0.y * v0.y) + (v0.z * v0.z + v0.w * v0.w)) + ((v1.x * v1.x + v1.y * v1.y) + (v1.z * v1.z + v1.w * v1.w));
;                         u32x4 w; w.x = cvt_pk_bf16(v0.x, v0.y); w.y = cvt_pk_bf16(v0.z, v0.w); w.z = cvt_pk_bf16(v1.x, v1.y); w.w = cvt_pk_bf16(v1.z, v1.w); EPI_ST((u32x4*)(xb + bj * 128), w); }
;                     if (SS) { ss += __shfl_xor(ss, 16); ss += __shfl_xor(ss, 32); if (fq == 0) SS[(size_t)row * 32 + u.pn * 4 + wc] = ss; } }
;                 asm volatile("" ::: "memory"); }
	v_pk_add_f32 v[108:109], v[108:109], v[60:61]
	v_pk_add_f32 v[110:111], v[110:111], v[62:63]
	v_pk_add_f32 v[104:105], v[104:105], v[56:57]
	v_pk_add_f32 v[106:107], v[106:107], v[58:59]
	v_pk_add_f32 v[100:101], v[100:101], v[28:29]
	v_pk_add_f32 v[102:103], v[102:103], v[30:31]
	v_pk_add_f32 v[96:97], v[96:97], v[24:25]
	v_pk_add_f32 v[98:99], v[98:99], v[26:27]
	v_mul_f32_e32 v250, v109, v109
	v_mul_f32_e32 v252, v111, v111
	v_fmac_f32_e32 v250, v108, v108
	v_fmac_f32_e32 v252, v110, v110
	v_mul_f32_e32 v253, v105, v105
	v_mul_f32_e32 v254, v107, v107
	v_add_f32_e32 v250, v250, v252
	v_fmac_f32_e32 v253, v104, v104
	v_fmac_f32_e32 v254, v106, v106
	v_add_f32_e32 v253, v253, v254
	v_add_f32_e32 v250, v250, v253
	v_mul_f32_e32 v251, v101, v101
	v_mul_f32_e32 v252, v103, v103
	v_fmac_f32_e32 v251, v100, v100
	v_fmac_f32_e32 v252, v102, v102
	v_mul_f32_e32 v253, v97, v97
	v_mul_f32_e32 v254, v99, v99
	v_add_f32_e32 v251, v251, v252
	v_fmac_f32_e32 v253, v96, v96
	v_fmac_f32_e32 v254, v98, v98
	v_add_f32_e32 v253, v253, v254
	v_add_f32_e32 v251, v251, v253
	v_cvt_pk_bf16_f32 v60, v108, v109
	v_cvt_pk_bf16_f32 v61, v110, v111
	v_cvt_pk_bf16_f32 v62, v104, v105
	v_cvt_pk_bf16_f32 v63, v106, v107
	v_cvt_pk_bf16_f32 v28, v100, v101
	v_cvt_pk_bf16_f32 v29, v102, v103
	v_cvt_pk_bf16_f32 v30, v96, v97
	v_cvt_pk_bf16_f32 v31, v98, v99
	v_add_f32_e32 v56, v250, v251
	s_add_u32 s98, s26, 0x90000
	s_addc_u32 s99, s27, 0
	global_store_dwordx4 v247, v[60:63], s[98:99]
	global_store_dwordx4 v247, v[28:31], s[98:99] offset:256
	s_waitcnt vmcnt(10)
	v_pk_add_f32 v[92:93], v[92:93], v[40:41]
	v_pk_add_f32 v[94:95], v[94:95], v[42:43]
	v_pk_add_f32 v[88:89], v[88:89], v[32:33]
	v_pk_add_f32 v[90:91], v[90:91], v[34:35]
	v_pk_add_f32 v[84:85], v[84:85], v[12:13]
	v_pk_add_f32 v[86:87], v[86:87], v[14:15]
	v_pk_add_f32 v[80:81], v[80:81], v[8:9]
	v_pk_add_f32 v[82:83], v[82:83], v[10:11]
	v_mul_f32_e32 v250, v93, v93
	v_mul_f32_e32 v252, v95, v95
	v_fmac_f32_e32 v250, v92, v92
	v_fmac_f32_e32 v252, v94, v94
	v_mul_f32_e32 v253, v89, v89
	v_mul_f32_e32 v254, v91, v91
	v_add_f32_e32 v250, v250, v252
	v_fmac_f32_e32 v253, v88, v88
	v_fmac_f32_e32 v254, v90, v90
	v_add_f32_e32 v253, v253, v254
	v_add_f32_e32 v250, v250, v253
	v_mul_f32_e32 v251, v85, v85
	v_mul_f32_e32 v252, v87, v87
	v_fmac_f32_e32 v251, v84, v84
	v_fmac_f32_e32 v252, v86, v86
	v_mul_f32_e32 v253, v81, v81
	v_mul_f32_e32 v254, v83, v83
	v_add_f32_e32 v251, v251, v252
	v_fmac_f32_e32 v253, v80, v80
	v_fmac_f32_e32 v254, v82, v82
	v_add_f32_e32 v253, v253, v254
	v_add_f32_e32 v251, v251, v253
	v_cvt_pk_bf16_f32 v40, v92, v93
	v_cvt_pk_bf16_f32 v41, v94, v95
	v_cvt_pk_bf16_f32 v42, v88, v89
	v_cvt_pk_bf16_f32 v43, v90, v91
	v_cvt_pk_bf16_f32 v12, v84, v85
	v_cvt_pk_bf16_f32 v13, v86, v87
	v_cvt_pk_bf16_f32 v14, v80, v81
	v_cvt_pk_bf16_f32 v15, v82, v83
	v_add_f32_e32 v32, v250, v251
	s_add_u32 s98, s26, 0xa0000
	s_addc_u32 s99, s27, 0
	global_store_dwordx4 v247, v[40:43], s[98:99]
	global_store_dwordx4 v247, v[12:15], s[98:99] offset:256
	s_waitcnt vmcnt(6)
	v_pk_add_f32 v[76:77], v[76:77], v[20:21]
	v_pk_add_f32 v[78:79], v[78:79], v[22:23]
	v_pk_add_f32 v[72:73], v[72:73], v[16:17]
	v_pk_add_f32 v[74:75], v[74:75], v[18:19]
	v_pk_add_f32 v[52:53], v[52:53], v[4:5]
	v_pk_add_f32 v[54:55], v[54:55], v[6:7]
	v_pk_add_f32 v[36:37], v[36:37], v[0:1]
	v_pk_add_f32 v[38:39], v[38:39], v[2:3]
	v_mul_f32_e32 v250, v77, v77
	v_mul_f32_e32 v252, v79, v79
	v_fmac_f32_e32 v250, v76, v76
	v_fmac_f32_e32 v252, v78, v78
	v_mul_f32_e32 v253, v73, v73
	v_mul_f32_e32 v254, v75, v75
	v_add_f32_e32 v250, v250, v252
	v_fmac_f32_e32 v253, v72, v72
	v_fmac_f32_e32 v254, v74, v74
	v_add_f32_e32 v253, v253, v254
	v_add_f32_e32 v250, v250, v253
	v_mul_f32_e32 v251, v53, v53
	v_mul_f32_e32 v252, v55, v55
	v_fmac_f32_e32 v251, v52, v52
	v_fmac_f32_e32 v252, v54, v54
	v_mul_f32_e32 v253, v37, v37
	v_mul_f32_e32 v254, v39, v39
	v_add_f32_e32 v251, v251, v252
	v_fmac_f32_e32 v253, v36, v36
	v_fmac_f32_e32 v254, v38, v38
	v_add_f32_e32 v253, v253, v254
	v_add_f32_e32 v251, v251, v253
	v_cvt_pk_bf16_f32 v20, v76, v77
	v_cvt_pk_bf16_f32 v21, v78, v79
	v_cvt_pk_bf16_f32 v22, v72, v73
	v_cvt_pk_bf16_f32 v23, v74, v75
	v_cvt_pk_bf16_f32 v4, v52, v53
	v_cvt_pk_bf16_f32 v5, v54, v55
	v_cvt_pk_bf16_f32 v6, v36, v37
	v_cvt_pk_bf16_f32 v7, v38, v39
	v_add_f32_e32 v16, v250, v251
	s_add_u32 s98, s26, 0xb0000
	s_addc_u32 s99, s27, 0
	global_store_dwordx4 v247, v[20:23], s[98:99]
	global_store_dwordx4 v247, v[4:7], s[98:99] offset:256
	ds_bpermute_b32 v133, v166, v132
	ds_bpermute_b32 v155, v166, v154
	ds_bpermute_b32 v187, v166, v186
	ds_bpermute_b32 v203, v166, v202
	ds_bpermute_b32 v65, v166, v64
	ds_bpermute_b32 v57, v166, v56
	ds_bpermute_b32 v33, v166, v32
	ds_bpermute_b32 v17, v166, v16
	v_cmp_eq_u32_e64 s[42:43], 0, v163
	s_waitcnt lgkmcnt(0)
	v_add_f32_e32 v132, v132, v133
	v_add_f32_e32 v154, v154, v155
	v_add_f32_e32 v186, v186, v187
	v_add_f32_e32 v202, v202, v203
	v_add_f32_e32 v64, v64, v65
	v_add_f32_e32 v56, v56, v57
	v_add_f32_e32 v32, v32, v33
	v_add_f32_e32 v16, v16, v17
	ds_bpermute_b32 v133, v167, v132
	ds_bpermute_b32 v155, v167, v154
	ds_bpermute_b32 v187, v167, v186
	ds_bpermute_b32 v203, v167, v202
	ds_bpermute_b32 v65, v167, v64
	ds_bpermute_b32 v57, v167, v56
	ds_bpermute_b32 v33, v167, v32
	ds_bpermute_b32 v17, v167, v16
	s_waitcnt lgkmcnt(0)
	v_add_f32_e32 v132, v132, v133
	v_add_f32_e32 v154, v154, v155
	v_add_f32_e32 v186, v186, v187
	v_add_f32_e32 v202, v202, v203
	v_add_f32_e32 v64, v64, v65
	v_add_f32_e32 v56, v56, v57
	v_add_f32_e32 v32, v32, v33
	v_add_f32_e32 v16, v16, v17
	s_and_saveexec_b64 s[6:7], s[42:43]
	global_store_dword v255, v132, s[100:101]
	s_add_u32 s98, s100, 0x800
	s_addc_u32 s99, s101, 0
	global_store_dword v255, v154, s[98:99]
	s_add_u32 s98, s100, 0x1000
	s_addc_u32 s99, s101, 0
	global_store_dword v255, v186, s[98:99]
	s_add_u32 s98, s100, 0x1800
	s_addc_u32 s99, s101, 0
	global_store_dword v255, v202, s[98:99]
	s_add_u32 s98, s100, 0x4000
	s_addc_u32 s99, s101, 0
	global_store_dword v255, v64, s[98:99]
	s_add_u32 s98, s100, 0x4800
	s_addc_u32 s99, s101, 0
	global_store_dword v255, v56, s[98:99]
	s_add_u32 s98, s100, 0x5000
	s_addc_u32 s99, s101, 0
	global_store_dword v255, v32, s[98:99]
	s_add_u32 s98, s100, 0x5800
	s_addc_u32 s99, s101, 0
	global_store_dword v255, v16, s[98:99]
	s_or_b64 exec, exec, s[6:7]
	s_branch .Lres1_done
; __device__ __forceinline__ unsigned cvt_pk_bf16(float lo, float hi) { unsigned r; asm volatile("v_cvt_pk_bf16_f32 %0, %1, %2" : "=v"(r) : "v"(lo), "v"(hi)); return r; }
; #define EPI_ST(p, v) __builtin_nontemporal_store((v), (p))
; __device__ __forceinline__ float bf_lo(unsigned w) { return __uint_as_float(w << 16); }
; __device__ __forceinline__ float bf_hi(unsigned w) { return __uint_as_float(w & 0xffff0000u); }
;     __device__ __forceinline__ void operator()(const f32x4 (&acc)[2][2][4][2], const pg8::Unit& u, int wr, int wc, int fr, int fq) const {
;     ...
;                 { bf16_t* xb = XB + (size_t)row * DM + col0; float ss = 0.f;
; #pragma unroll
;                     for (int bj = 0; bj < 2; ++bj) { f32x4 b0, b1;
;                         if (baseP) { const float* bp = baseP + (size_t)row * DM + col0 + bj * 128; b0 = *(const f32x4*)bp; b1 = *(const f32x4*)(bp + 4); }
;                         else { const u32x4 bw = *(const u32x4*)(xb + bj * 128); b0 = (f32x4){bf_lo(bw.x), bf_hi(bw.x), bf_lo(bw.y), bf_hi(bw.y)}; b1 = (f32x4){bf_lo(bw.z), bf_hi(bw.z), bf_lo(bw.w), bf_hi(bw.w)}; }
;                         const f32x4 v0 = b0 + acc[ai][bj][m][0], v1 = b1 + acc[ai][bj][m][1];
;                         ss += ((v0.x * v0.x + v0.y * v0.y) + (v0.z * v0.z + v0.w * v0.w)) + ((v1.x * v1.x + v1.y * v1.y) + (v1.z * v1.z + v1.w * v1.w));
;                         u32x4 w; w.x = cvt_pk_bf16(v0.x, v0.y); w.y = cvt_pk_bf16(v0.z, v0.w); w.z = cvt_pk_bf16(v1.x, v1.y); w.w = cvt_pk_bf16(v1.z, v1.w); EPI_ST((u32x4*)(xb + bj * 128), w); }
.Lres1_bf16:
	global_load_dwordx4 v[128:131], v247, s[26:27]
	global_load_dwordx4 v[132:135], v247, s[26:27] offset:256
	s_add_u32 s98, s26, 0x10000
	s_addc_u32 s99, s27, 0
	global_load_dwordx4 v[142:145], v247, s[98:99]
	global_load_dwordx4 v[146:149], v247, s[98:99] offset:256
	s_add_u32 s98, s26, 0x20000
	s_addc_u32 s99, s27, 0
	global_load_dwordx4 v[150:153], v247, s[98:99]
	global_load_dwordx4 v[154:157], v247, s[98:99] offset:256
	s_add_u32 s98, s26, 0x30000
	s_addc_u32 s99, s27, 0
	global_load_dwordx4 v[158:161], v247, s[98:99]
	global_load_dwordx4 v[178:181], v247, s[98:99] offset:256
	s_add_u32 s98, s26, 0x80000
	s_addc_u32 s99, s27, 0
	global_load_dwordx4 v[182:185], v247, s[98:99]
	global_load_dwordx4 v[186:189], v247, s[98:99] offset:256
	s_add_u32 s98, s26, 0x90000
	s_addc_u32 s99, s27, 0
	global_load_dwordx4 v[190:193], v247, s[98:99]
	global_load_dwordx4 v[194:197], v247, s[98:99] offset:256
	s_add_u32 s98, s26, 0xa0000
	s_addc_u32 s99, s27, 0
	global_load_dwordx4 v[198:201], v247, s[98:99]
	global_load_dwordx4 v[202:205], v247, s[98:99] offset:256
	s_add_u32 s98, s26, 0xb0000
	s_addc_u32 s99, s27, 0
	global_load_dwordx4 v[206:209], v247, s[98:99]
	global_load_dwordx4 v[226:229], v247, s[98:99] offset:256
	s_waitcnt vmcnt(14)
	v_lshlrev_b32_e32 v248, 16, v128
	v_and_b32_e32 v249, 0xffff0000, v128
	v_lshlrev_b32_e32 v250, 16, v129
	v_and_b32_e32 v251, 0xffff0000, v129
	v_pk_add_f32 v[68:69], v[68:69], v[248:249]
	v_pk_add_f32 v[70:71], v[70:71], v[250:251]
	v_lshlrev_b32_e32 v248, 16, v130
	v_and_b32_e32 v249, 0xffff0000, v130
	v_lshlrev_b32_e32 v250, 16, v131
	v_and_b32_e32 v251, 0xffff0000, v131
	v_pk_add_f32 v[64:65], v[64:65], v[248:249]
	v_pk_add_f32 v[66:67], v[66:67], v[250:251]
	v_lshlrev_b32_e32 v248, 16, v132
	v_and_b32_e32 v249, 0xffff0000, v132
	v_lshlrev_b32_e32 v250, 16, v133
	v_and_b32_e32 v251, 0xffff0000, v133
	v_pk_add_f32 v[48:49], v[48:49], v[248:249]
	v_pk_add_f32 v[50:51], v[50:51], v[250:251]
	v_lshlrev_b32_e32 v248, 16, v134
	v_and_b32_e32 v249, 0xffff0000, v134
	v_lshlrev_b32_e32 v250, 16, v135
	v_and_b32_e32 v251, 0xffff0000, v135
	v_pk_add_f32 v[44:45], v[44:45], v[248:249]
	v_pk_add_f32 v[46:47], v[46:47], v[250:251]
	v_mul_f32_e32 v250, v69, v69
	v_mul_f32_e32 v252, v71, v71
	v_fmac_f32_e32 v250, v68, v68
	v_fmac_f32_e32 v252, v70, v70
	v_mul_f32_e32 v253, v65, v65
	v_mul_f32_e32 v254, v67, v67
	v_add_f32_e32 v250, v250, v252
	v_fmac_f32_e32 v253, v64, v64
	v_fmac_f32_e32 v254, v66, v66
	v_add_f32_e32 v253, v253, v254
	v_add_f32_e32 v250, v250, v253
	v_mul_f32_e32 v251, v49, v49
	v_mul_f32_e32 v252, v51, v51
	v_fmac_f32_e32 v251, v48, v48
	v_fmac_f32_e32 v252, v50, v50
	v_mul_f32_e32 v253, v45, v45
	v_mul_f32_e32 v254, v47, v47
	v_add_f32_e32 v251, v251, v252
	v_fmac_f32_e32 v253, v44, v44
	v_fmac_f32_e32 v254, v46, v46
	v_add_f32_e32 v253, v253, v254
	v_add_f32_e32 v251, v251, v253
	v_cvt_pk_bf16_f32 v128, v68, v69
	v_cvt_pk_bf16_f32 v129, v70, v71
	v_cvt_pk_bf16_f32 v130, v64, v65
	v_cvt_pk_bf16_f32 v131, v66, v67
	v_cvt_pk_bf16_f32 v132, v48, v49
	v_cvt_pk_bf16_f32 v133, v50, v51
	v_cvt_pk_bf16_f32 v134, v44, v45
	v_cvt_pk_bf16_f32 v135, v46, v47
	v_add_f32_e32 v68, v250, v251
	global_store_dwordx4 v247, v[128:131], s[26:27]
	global_store_dwordx4 v247, v[132:135], s[26:27] offset:256
	s_waitcnt vmcnt(14)
	v_lshlrev_b32_e32 v248, 16, v142
	v_and_b32_e32 v249, 0xffff0000, v142
	v_lshlrev_b32_e32 v250, 16, v143
	v_and_b32_e32 v251, 0xffff0000, v143
	v_pk_add_f32 v[60:61], v[60:61], v[248:249]
	v_pk_add_f32 v[62:63], v[62:63], v[250:251]
	v_lshlrev_b32_e32 v248, 16, v144
	v_and_b32_e32 v249, 0xffff0000, v144
	v_lshlrev_b32_e32 v250, 16, v145
	v_and_b32_e32 v251, 0xffff0000, v145
	v_pk_add_f32 v[56:57], v[56:57], v[248:249]
	v_pk_add_f32 v[58:59], v[58:59], v[250:251]
	v_lshlrev_b32_e32 v248, 16, v146
	v_and_b32_e32 v249, 0xffff0000, v146
	v_lshlrev_b32_e32 v250, 16, v147
	v_and_b32_e32 v251, 0xffff0000, v147
	v_pk_add_f32 v[28:29], v[28:29], v[248:249]
	v_pk_add_f32 v[30:31], v[30:31], v[250:251]
	v_lshlrev_b32_e32 v248, 16, v148
	v_and_b32_e32 v249, 0xffff0000, v148
	v_lshlrev_b32_e32 v250, 16, v149
	v_and_b32_e32 v251, 0xffff0000, v149
	v_pk_add_f32 v[24:25], v[24:25], v[248:249]
	v_pk_add_f32 v[26:27], v[26:27], v[250:251]
	v_mul_f32_e32 v250, v61, v61
	v_mul_f32_e32 v252, v63, v63
	v_fmac_f32_e32 v250, v60, v60
	v_fmac_f32_e32 v252, v62, v62
	v_mul_f32_e32 v253, v57, v57
	v_mul_f32_e32 v254, v59, v59
	v_add_f32_e32 v250, v250, v252
	v_fmac_f32_e32 v253, v56, v56
	v_fmac_f32_e32 v254, v58, v58
	v_add_f32_e32 v253, v253, v254
	v_add_f32_e32 v250, v250, v253
	v_mul_f32_e32 v251, v29, v29
	v_mul_f32_e32 v252, v31, v31
	v_fmac_f32_e32 v251, v28, v28
	v_fmac_f32_e32 v252, v30, v30
	v_mul_f32_e32 v253, v25, v25
	v_mul_f32_e32 v254, v27, v27
	v_add_f32_e32 v251, v251, v252
	v_fmac_f32_e32 v253, v24, v24
	v_fmac_f32_e32 v254, v26, v26
	v_add_f32_e32 v253, v253, v254
	v_add_f32_e32 v251, v251, v253
	v_cvt_pk_bf16_f32 v142, v60, v61
	v_cvt_pk_bf16_f32 v143, v62, v63
	v_cvt_pk_bf16_f32 v144, v56, v57
	v_cvt_pk_bf16_f32 v145, v58, v59
	v_cvt_pk_bf16_f32 v146, v28, v29
	v_cvt_pk_bf16_f32 v147, v30, v31
	v_cvt_pk_bf16_f32 v148, v24, v25
	v_cvt_pk_bf16_f32 v149, v26, v27
	v_add_f32_e32 v60, v250, v251
	s_add_u32 s98, s26, 0x10000
	s_addc_u32 s99, s27, 0
	global_store_dwordx4 v247, v[142:145], s[98:99]
	global_store_dwordx4 v247, v[146:149], s[98:99] offset:256
	s_waitcnt vmcnt(14)
; __device__ __forceinline__ unsigned cvt_pk_bf16(float lo, float hi) { unsigned r; asm volatile("v_cvt_pk_bf16_f32 %0, %1, %2" : "=v"(r) : "v"(lo), "v"(hi)); return r; }
; #define EPI_ST(p, v) __builtin_nontemporal_store((v), (p))
; __device__ __forceinline__ float bf_lo(unsigned w) { return __uint_as_float(w << 16); }
; __device__ __forceinline__ float bf_hi(unsigned w) { return __uint_as_float(w & 0xffff0000u); }
;     __device__ __forceinline__ void operator()(const f32x4 (&acc)[2][2][4][2], const pg8::Unit& u, int wr, int wc, int fr, int fq) const {
;     ...
;                     for (int bj = 0; bj < 2; ++bj) { f32x4 b0, b1;
;                         if (baseP) { const float* bp = baseP + (size_t)row * DM + col0 + bj * 128; b0 = *(const f32x4*)bp; b1 = *(const f32x4*)(bp + 4); }
;                         else { const u32x4 bw = *(const u32x4*)(xb + bj * 128); b0 = (f32x4){bf_lo(bw.x), bf_hi(bw.x), bf_lo(bw.y), bf_hi(bw.y)}; b1 = (f32x4){bf_lo(bw.z), bf_hi(bw.z), bf_lo(bw.w), bf_hi(bw.w)}; }
;                         const f32x4 v0 = b0 + acc[ai][bj][m][0], v1 = b1 + acc[ai][bj][m][1];
;                         ss += ((v0.x * v0.x + v0.y * v0.y) + (v0.z * v0.z + v0.w * v0.w)) + ((v1.x * v1.x + v1.y * v1.y) + (v1.z * v1.z + v1.w * v1.w));
;                         u32x4 w; w.x = cvt_pk_bf16(v0.x, v0.y); w.y = cvt_pk_bf16(v0.z, v0.w); w.z = cvt_pk_bf16(v1.x, v1.y); w.w = cvt_pk_bf16(v1.z, v1.w); EPI_ST((u32x4*)(xb + bj * 128), w); }
	v_lshlrev_b32_e32 v248, 16, v150
	v_and_b32_e32 v249, 0xffff0000, v150
	v_lshlrev_b32_e32 v250, 16, v151
	v_and_b32_e32 v251, 0xffff0000, v151
	v_pk_add_f32 v[40:41], v[40:41], v[248:249]
	v_pk_add_f32 v[42:43], v[42:43], v[250:251]
	v_lshlrev_b32_e32 v248, 16, v152
	v_and_b32_e32 v249, 0xffff0000, v152
	v_lshlrev_b32_e32 v250, 16, v153
	v_and_b32_e32 v251, 0xffff0000, v153
	v_pk_add_f32 v[32:33], v[32:33], v[248:249]
	v_pk_add_f32 v[34:35], v[34:35], v[250:251]
	v_lshlrev_b32_e32 v248, 16, v154
	v_and_b32_e32 v249, 0xffff0000, v154
	v_lshlrev_b32_e32 v250, 16, v155
	v_and_b32_e32 v251, 0xffff0000, v155
	v_pk_add_f32 v[12:13], v[12:13], v[248:249]
	v_pk_add_f32 v[14:15], v[14:15], v[250:251]
	v_lshlrev_b32_e32 v248, 16, v156
	v_and_b32_e32 v249, 0xffff0000, v156
	v_lshlrev_b32_e32 v250, 16, v157
	v_and_b32_e32 v251, 0xffff0000, v157
	v_pk_add_f32 v[8:9], v[8:9], v[248:249]
	v_pk_add_f32 v[10:11], v[10:11], v[250:251]
	v_mul_f32_e32 v250, v41, v41
	v_mul_f32_e32 v252, v43, v43
	v_fmac_f32_e32 v250, v40, v40
	v_fmac_f32_e32 v252, v42, v42
	v_mul_f32_e32 v253, v33, v33
	v_mul_f32_e32 v254, v35, v35
	v_add_f32_e32 v250, v250, v252
	v_fmac_f32_e32 v253, v32, v32
	v_fmac_f32_e32 v254, v34, v34
	v_add_f32_e32 v253, v253, v254
	v_add_f32_e32 v250, v250, v253
	v_mul_f32_e32 v251, v13, v13
	v_mul_f32_e32 v252, v15, v15
	v_fmac_f32_e32 v251, v12, v12
	v_fmac_f32_e32 v252, v14, v14
	v_mul_f32_e32 v253, v9, v9
	v_mul_f32_e32 v254, v11, v11
	v_add_f32_e32 v251, v251, v252
	v_fmac_f32_e32 v253, v8, v8
	v_fmac_f32_e32 v254, v10, v10
	v_add_f32_e32 v253, v253, v254
	v_add_f32_e32 v251, v251, v253
	v_cvt_pk_bf16_f32 v150, v40, v41
	v_cvt_pk_bf16_f32 v151, v42, v43
	v_cvt_pk_bf16_f32 v152, v32, v33
	v_cvt_pk_bf16_f32 v153, v34, v35
	v_cvt_pk_bf16_f32 v154, v12, v13
	v_cvt_pk_bf16_f32 v155, v14, v15
	v_cvt_pk_bf16_f32 v156, v8, v9
	v_cvt_pk_bf16_f32 v157, v10, v11
	v_add_f32_e32 v40, v250, v251
	s_add_u32 s98, s26, 0x20000
	s_addc_u32 s99, s27, 0
	global_store_dwordx4 v247, v[150:153], s[98:99]
	global_store_dwordx4 v247, v[154:157], s[98:99] offset:256
	s_waitcnt vmcnt(14)
	v_lshlrev_b32_e32 v248, 16, v158
	v_and_b32_e32 v249, 0xffff0000, v158
	v_lshlrev_b32_e32 v250, 16, v159
	v_and_b32_e32 v251, 0xffff0000, v159
	v_pk_add_f32 v[20:21], v[20:21], v[248:249]
	v_pk_add_f32 v[22:23], v[22:23], v[250:251]
	v_lshlrev_b32_e32 v248, 16, v160
	v_and_b32_e32 v249, 0xffff0000, v160
	v_lshlrev_b32_e32 v250, 16, v161
	v_and_b32_e32 v251, 0xffff0000, v161
	v_pk_add_f32 v[16:17], v[16:17], v[248:249]
	v_pk_add_f32 v[18:19], v[18:19], v[250:251]
	v_lshlrev_b32_e32 v248, 16, v178
	v_and_b32_e32 v249, 0xffff0000, v178
	v_lshlrev_b32_e32 v250, 16, v179
	v_and_b32_e32 v251, 0xffff0000, v179
	v_pk_add_f32 v[4:5], v[4:5], v[248:249]
	v_pk_add_f32 v[6:7], v[6:7], v[250:251]
	v_lshlrev_b32_e32 v248, 16, v180
	v_and_b32_e32 v249, 0xffff0000, v180
	v_lshlrev_b32_e32 v250, 16, v181
	v_and_b32_e32 v251, 0xffff0000, v181
	v_pk_add_f32 v[0:1], v[0:1], v[248:249]
	v_pk_add_f32 v[2:3], v[2:3], v[250:251]
	v_mul_f32_e32 v250, v21, v21
	v_mul_f32_e32 v252, v23, v23
	v_fmac_f32_e32 v250, v20, v20
	v_fmac_f32_e32 v252, v22, v22
	v_mul_f32_e32 v253, v17, v17
	v_mul_f32_e32 v254, v19, v19
	v_add_f32_e32 v250, v250, v252
	v_fmac_f32_e32 v253, v16, v16
	v_fmac_f32_e32 v254, v18, v18
	v_add_f32_e32 v253, v253, v254
	v_add_f32_e32 v250, v250, v253
	v_mul_f32_e32 v251, v5, v5
	v_mul_f32_e32 v252, v7, v7
	v_fmac_f32_e32 v251, v4, v4
	v_fmac_f32_e32 v252, v6, v6
	v_mul_f32_e32 v253, v1, v1
	v_mul_f32_e32 v254, v3, v3
	v_add_f32_e32 v251, v251, v252
	v_fmac_f32_e32 v253, v0, v0
	v_fmac_f32_e32 v254, v2, v2
	v_add_f32_e32 v253, v253, v254
	v_add_f32_e32 v251, v251, v253
	v_cvt_pk_bf16_f32 v158, v20, v21
	v_cvt_pk_bf16_f32 v159, v22, v23
	v_cvt_pk_bf16_f32 v160, v16, v17
	v_cvt_pk_bf16_f32 v161, v18, v19
	v_cvt_pk_bf16_f32 v178, v4, v5
	v_cvt_pk_bf16_f32 v179, v6, v7
	v_cvt_pk_bf16_f32 v180, v0, v1
	v_cvt_pk_bf16_f32 v181, v2, v3
	v_add_f32_e32 v20, v250, v251
	s_add_u32 s98, s26, 0x30000
	s_addc_u32 s99, s27, 0
	global_store_dwordx4 v247, v[158:161], s[98:99]
	global_store_dwordx4 v247, v[178:181], s[98:99] offset:256
	s_waitcnt vmcnt(14)
	v_lshlrev_b32_e32 v248, 16, v182
	v_and_b32_e32 v249, 0xffff0000, v182
	v_lshlrev_b32_e32 v250, 16, v183
	v_and_b32_e32 v251, 0xffff0000, v183
	v_pk_add_f32 v[124:125], v[124:125], v[248:249]
	v_pk_add_f32 v[126:127], v[126:127], v[250:251]
	v_lshlrev_b32_e32 v248, 16, v184
	v_and_b32_e32 v249, 0xffff0000, v184
	v_lshlrev_b32_e32 v250, 16, v185
	v_and_b32_e32 v251, 0xffff0000, v185
	v_pk_add_f32 v[120:121], v[120:121], v[248:249]
	v_pk_add_f32 v[122:123], v[122:123], v[250:251]
	v_lshlrev_b32_e32 v248, 16, v186
	v_and_b32_e32 v249, 0xffff0000, v186
	v_lshlrev_b32_e32 v250, 16, v187
	v_and_b32_e32 v251, 0xffff0000, v187
	v_pk_add_f32 v[116:117], v[116:117], v[248:249]
	v_pk_add_f32 v[118:119], v[118:119], v[250:251]
	v_lshlrev_b32_e32 v248, 16, v188
	v_and_b32_e32 v249, 0xffff0000, v188
	v_lshlrev_b32_e32 v250, 16, v189
	v_and_b32_e32 v251, 0xffff0000, v189
	v_pk_add_f32 v[112:113], v[112:113], v[248:249]
	v_pk_add_f32 v[114:115], v[114:115], v[250:251]
	v_mul_f32_e32 v250, v125, v125
	v_mul_f32_e32 v252, v127, v127
	v_fmac_f32_e32 v250, v124, v124
	v_fmac_f32_e32 v252, v126, v126
	v_mul_f32_e32 v253, v121, v121
	v_mul_f32_e32 v254, v123, v123
	v_add_f32_e32 v250, v250, v252
	v_fmac_f32_e32 v253, v120, v120
	v_fmac_f32_e32 v254, v122, v122
	v_add_f32_e32 v253, v253, v254
	v_add_f32_e32 v250, v250, v253
	v_mul_f32_e32 v251, v117, v117
	v_mul_f32_e32 v252, v119, v119
	v_fmac_f32_e32 v251, v116, v116
	v_fmac_f32_e32 v252, v118, v118
	v_mul_f32_e32 v253, v113, v113
	v_mul_f32_e32 v254, v115, v115
	v_add_f32_e32 v251, v251, v252
	v_fmac_f32_e32 v253, v112, v112
	v_fmac_f32_e32 v254, v114, v114
	v_add_f32_e32 v253, v253, v254
	v_add_f32_e32 v251, v251, v253
	v_cvt_pk_bf16_f32 v182, v124, v125
	v_cvt_pk_bf16_f32 v183, v126, v127
	v_cvt_pk_bf16_f32 v184, v120, v121
	v_cvt_pk_bf16_f32 v185, v122, v123
	v_cvt_pk_bf16_f32 v186, v116, v117
	v_cvt_pk_bf16_f32 v187, v118, v119
	v_cvt_pk_bf16_f32 v188, v112, v113
	v_cvt_pk_bf16_f32 v189, v114, v115
	v_add_f32_e32 v124, v250, v251
	s_add_u32 s98, s26, 0x80000
	s_addc_u32 s99, s27, 0
	global_store_dwordx4 v247, v[182:185], s[98:99]
	global_store_dwordx4 v247, v[186:189], s[98:99] offset:256
	s_waitcnt vmcnt(14)
; __device__ __forceinline__ unsigned cvt_pk_bf16(float lo, float hi) { unsigned r; asm volatile("v_cvt_pk_bf16_f32 %0, %1, %2" : "=v"(r) : "v"(lo), "v"(hi)); return r; }
; #define EPI_ST(p, v) __builtin_nontemporal_store((v), (p))
; __device__ __forceinline__ float bf_lo(unsigned w) { return __uint_as_float(w << 16); }
; __device__ __forceinline__ float bf_hi(unsigned w) { return __uint_as_float(w & 0xffff0000u); }
;     __device__ __forceinline__ void operator()(const f32x4 (&acc)[2][2][4][2], const pg8::Unit& u, int wr, int wc, int fr, int fq) const {
;     ...
;                     for (int bj = 0; bj < 2; ++bj) { f32x4 b0, b1;
;                         if (baseP) { const float* bp = baseP + (size_t)row * DM + col0 + bj * 128; b0 = *(const f32x4*)bp; b1 = *(const f32x4*)(bp + 4); }
;                         else { const u32x4 bw = *(const u32x4*)(xb + bj * 128); b0 = (f32x4){bf_lo(bw.x), bf_hi(bw.x), bf_lo(bw.y), bf_hi(bw.y)}; b1 = (f32x4){bf_lo(bw.z), bf_hi(bw.z), bf_lo(bw.w), bf_hi(bw.w)}; }
;                         const f32x4 v0 = b0 + acc[ai][bj][m][0], v1 = b1 + acc[ai][bj][m][1];
;                         ss += ((v0.x * v0.x + v0.y * v0.y) + (v0.z * v0.z + v0.w * v0.w)) + ((v1.x * v1.x + v1.y * v1.y) + (v1.z * v1.z + v1.w * v1.w));
;                         u32x4 w; w.x = cvt_pk_bf16(v0.x, v0.y); w.y = cvt_pk_bf16(v0.z, v0.w); w.z = cvt_pk_bf16(v1.x, v1.y); w.w = cvt_pk_bf16(v1.z, v1.w); EPI_ST((u32x4*)(xb + bj * 128), w); }
	v_lshlrev_b32_e32 v248, 16, v190
	v_and_b32_e32 v249, 0xffff0000, v190
	v_lshlrev_b32_e32 v250, 16, v191
	v_and_b32_e32 v251, 0xffff0000, v191
	v_pk_add_f32 v[108:109], v[108:109], v[248:249]
	v_pk_add_f32 v[110:111], v[110:111], v[250:251]
	v_lshlrev_b32_e32 v248, 16, v192
	v_and_b32_e32 v249, 0xffff0000, v192
	v_lshlrev_b32_e32 v250, 16, v193
	v_and_b32_e32 v251, 0xffff0000, v193
	v_pk_add_f32 v[104:105], v[104:105], v[248:249]
	v_pk_add_f32 v[106:107], v[106:107], v[250:251]
	v_lshlrev_b32_e32 v248, 16, v194
	v_and_b32_e32 v249, 0xffff0000, v194
	v_lshlrev_b32_e32 v250, 16, v195
	v_and_b32_e32 v251, 0xffff0000, v195
	v_pk_add_f32 v[100:101], v[100:101], v[248:249]
	v_pk_add_f32 v[102:103], v[102:103], v[250:251]
	v_lshlrev_b32_e32 v248, 16, v196
	v_and_b32_e32 v249, 0xffff0000, v196
	v_lshlrev_b32_e32 v250, 16, v197
	v_and_b32_e32 v251, 0xffff0000, v197
	v_pk_add_f32 v[96:97], v[96:97], v[248:249]
	v_pk_add_f32 v[98:99], v[98:99], v[250:251]
	v_mul_f32_e32 v250, v109, v109
	v_mul_f32_e32 v252, v111, v111
	v_fmac_f32_e32 v250, v108, v108
	v_fmac_f32_e32 v252, v110, v110
	v_mul_f32_e32 v253, v105, v105
	v_mul_f32_e32 v254, v107, v107
	v_add_f32_e32 v250, v250, v252
	v_fmac_f32_e32 v253, v104, v104
	v_fmac_f32_e32 v254, v106, v106
	v_add_f32_e32 v253, v253, v254
	v_add_f32_e32 v250, v250, v253
	v_mul_f32_e32 v251, v101, v101
	v_mul_f32_e32 v252, v103, v103
	v_fmac_f32_e32 v251, v100, v100
	v_fmac_f32_e32 v252, v102, v102
	v_mul_f32_e32 v253, v97, v97
	v_mul_f32_e32 v254, v99, v99
	v_add_f32_e32 v251, v251, v252
	v_fmac_f32_e32 v253, v96, v96
	v_fmac_f32_e32 v254, v98, v98
	v_add_f32_e32 v253, v253, v254
	v_add_f32_e32 v251, v251, v253
	v_cvt_pk_bf16_f32 v190, v108, v109
	v_cvt_pk_bf16_f32 v191, v110, v111
	v_cvt_pk_bf16_f32 v192, v104, v105
	v_cvt_pk_bf16_f32 v193, v106, v107
	v_cvt_pk_bf16_f32 v194, v100, v101
	v_cvt_pk_bf16_f32 v195, v102, v103
	v_cvt_pk_bf16_f32 v196, v96, v97
	v_cvt_pk_bf16_f32 v197, v98, v99
	v_add_f32_e32 v108, v250, v251
	s_add_u32 s98, s26, 0x90000
	s_addc_u32 s99, s27, 0
	global_store_dwordx4 v247, v[190:193], s[98:99]
	global_store_dwordx4 v247, v[194:197], s[98:99] offset:256
	s_waitcnt vmcnt(14)
	v_lshlrev_b32_e32 v248, 16, v198
	v_and_b32_e32 v249, 0xffff0000, v198
	v_lshlrev_b32_e32 v250, 16, v199
	v_and_b32_e32 v251, 0xffff0000, v199
	v_pk_add_f32 v[92:93], v[92:93], v[248:249]
	v_pk_add_f32 v[94:95], v[94:95], v[250:251]
	v_lshlrev_b32_e32 v248, 16, v200
	v_and_b32_e32 v249, 0xffff0000, v200
	v_lshlrev_b32_e32 v250, 16, v201
	v_and_b32_e32 v251, 0xffff0000, v201
	v_pk_add_f32 v[88:89], v[88:89], v[248:249]
	v_pk_add_f32 v[90:91], v[90:91], v[250:251]
	v_lshlrev_b32_e32 v248, 16, v202
	v_and_b32_e32 v249, 0xffff0000, v202
	v_lshlrev_b32_e32 v250, 16, v203
	v_and_b32_e32 v251, 0xffff0000, v203
	v_pk_add_f32 v[84:85], v[84:85], v[248:249]
	v_pk_add_f32 v[86:87], v[86:87], v[250:251]
	v_lshlrev_b32_e32 v248, 16, v204
	v_and_b32_e32 v249, 0xffff0000, v204
	v_lshlrev_b32_e32 v250, 16, v205
	v_and_b32_e32 v251, 0xffff0000, v205
	v_pk_add_f32 v[80:81], v[80:81], v[248:249]
	v_pk_add_f32 v[82:83], v[82:83], v[250:251]
	v_mul_f32_e32 v250, v93, v93
	v_mul_f32_e32 v252, v95, v95
	v_fmac_f32_e32 v250, v92, v92
	v_fmac_f32_e32 v252, v94, v94
	v_mul_f32_e32 v253, v89, v89
	v_mul_f32_e32 v254, v91, v91
	v_add_f32_e32 v250, v250, v252
	v_fmac_f32_e32 v253, v88, v88
	v_fmac_f32_e32 v254, v90, v90
	v_add_f32_e32 v253, v253, v254
	v_add_f32_e32 v250, v250, v253
	v_mul_f32_e32 v251, v85, v85
	v_mul_f32_e32 v252, v87, v87
	v_fmac_f32_e32 v251, v84, v84
	v_fmac_f32_e32 v252, v86, v86
	v_mul_f32_e32 v253, v81, v81
	v_mul_f32_e32 v254, v83, v83
	v_add_f32_e32 v251, v251, v252
	v_fmac_f32_e32 v253, v80, v80
	v_fmac_f32_e32 v254, v82, v82
	v_add_f32_e32 v253, v253, v254
	v_add_f32_e32 v251, v251, v253
	v_cvt_pk_bf16_f32 v198, v92, v93
	v_cvt_pk_bf16_f32 v199, v94, v95
	v_cvt_pk_bf16_f32 v200, v88, v89
	v_cvt_pk_bf16_f32 v201, v90, v91
	v_cvt_pk_bf16_f32 v202, v84, v85
	v_cvt_pk_bf16_f32 v203, v86, v87
	v_cvt_pk_bf16_f32 v204, v80, v81
	v_cvt_pk_bf16_f32 v205, v82, v83
	v_add_f32_e32 v92, v250, v251
	s_add_u32 s98, s26, 0xa0000
	s_addc_u32 s99, s27, 0
	global_store_dwordx4 v247, v[198:201], s[98:99]
	global_store_dwordx4 v247, v[202:205], s[98:99] offset:256
	s_waitcnt vmcnt(14)
; __device__ __forceinline__ unsigned cvt_pk_bf16(float lo, float hi) { unsigned r; asm volatile("v_cvt_pk_bf16_f32 %0, %1, %2" : "=v"(r) : "v"(lo), "v"(hi)); return r; }
; #define EPI_ST(p, v) __builtin_nontemporal_store((v), (p))
; __device__ __forceinline__ float bf_lo(unsigned w) { return __uint_as_float(w << 16); }
; __device__ __forceinline__ float bf_hi(unsigned w) { return __uint_as_float(w & 0xffff0000u); }
;     __device__ __forceinline__ void operator()(const f32x4 (&acc)[2][2][4][2], const pg8::Unit& u, int wr, int wc, int fr, int fq) const {
;     ...
;                     for (int bj = 0; bj < 2; ++bj) { f32x4 b0, b1;
;                         if (baseP) { const float* bp = baseP + (size_t)row * DM + col0 + bj * 128; b0 = *(const f32x4*)bp; b1 = *(const f32x4*)(bp + 4); }
;                         else { const u32x4 bw = *(const u32x4*)(xb + bj * 128); b0 = (f32x4){bf_lo(bw.x), bf_hi(bw.x), bf_lo(bw.y), bf_hi(bw.y)}; b1 = (f32x4){bf_lo(bw.z), bf_hi(bw.z), bf_lo(bw.w), bf_hi(bw.w)}; }
;                         const f32x4 v0 = b0 + acc[ai][bj][m][0], v1 = b1 + acc[ai][bj][m][1];
;                         ss += ((v0.x * v0.x + v0.y * v0.y) + (v0.z * v0.z + v0.w * v0.w)) + ((v1.x * v1.x + v1.y * v1.y) + (v1.z * v1.z + v1.w * v1.w));
;                         u32x4 w; w.x = cvt_pk_bf16(v0.x, v0.y); w.y = cvt_pk_bf16(v0.z, v0.w); w.z = cvt_pk_bf16(v1.x, v1.y); w.w = cvt_pk_bf16(v1.z, v1.w); EPI_ST((u32x4*)(xb + bj * 128), w); }
;                     if (SS) { ss += __shfl_xor(ss, 16); ss += __shfl_xor(ss, 32); if (fq == 0) SS[(size_t)row * 32 + u.pn * 4 + wc] = ss; } }
;                 asm volatile("" ::: "memory"); }
	v_lshlrev_b32_e32 v248, 16, v206
	v_and_b32_e32 v249, 0xffff0000, v206
	v_lshlrev_b32_e32 v250, 16, v207
	v_and_b32_e32 v251, 0xffff0000, v207
	v_pk_add_f32 v[76:77], v[76:77], v[248:249]
	v_pk_add_f32 v[78:79], v[78:79], v[250:251]
	v_lshlrev_b32_e32 v248, 16, v208
	v_and_b32_e32 v249, 0xffff0000, v208
	v_lshlrev_b32_e32 v250, 16, v209
	v_and_b32_e32 v251, 0xffff0000, v209
	v_pk_add_f32 v[72:73], v[72:73], v[248:249]
	v_pk_add_f32 v[74:75], v[74:75], v[250:251]
	v_lshlrev_b32_e32 v248, 16, v226
	v_and_b32_e32 v249, 0xffff0000, v226
	v_lshlrev_b32_e32 v250, 16, v227
	v_and_b32_e32 v251, 0xffff0000, v227
	v_pk_add_f32 v[52:53], v[52:53], v[248:249]
	v_pk_add_f32 v[54:55], v[54:55], v[250:251]
	v_lshlrev_b32_e32 v248, 16, v228
	v_and_b32_e32 v249, 0xffff0000, v228
	v_lshlrev_b32_e32 v250, 16, v229
	v_and_b32_e32 v251, 0xffff0000, v229
	v_pk_add_f32 v[36:37], v[36:37], v[248:249]
	v_pk_add_f32 v[38:39], v[38:39], v[250:251]
	v_mul_f32_e32 v250, v77, v77
	v_mul_f32_e32 v252, v79, v79
	v_fmac_f32_e32 v250, v76, v76
	v_fmac_f32_e32 v252, v78, v78
	v_mul_f32_e32 v253, v73, v73
	v_mul_f32_e32 v254, v75, v75
	v_add_f32_e32 v250, v250, v252
	v_fmac_f32_e32 v253, v72, v72
	v_fmac_f32_e32 v254, v74, v74
	v_add_f32_e32 v253, v253, v254
	v_add_f32_e32 v250, v250, v253
	v_mul_f32_e32 v251, v53, v53
	v_mul_f32_e32 v252, v55, v55
	v_fmac_f32_e32 v251, v52, v52
	v_fmac_f32_e32 v252, v54, v54
	v_mul_f32_e32 v253, v37, v37
	v_mul_f32_e32 v254, v39, v39
	v_add_f32_e32 v251, v251, v252
	v_fmac_f32_e32 v253, v36, v36
	v_fmac_f32_e32 v254, v38, v38
	v_add_f32_e32 v253, v253, v254
	v_add_f32_e32 v251, v251, v253
	v_cvt_pk_bf16_f32 v206, v76, v77
	v_cvt_pk_bf16_f32 v207, v78, v79
	v_cvt_pk_bf16_f32 v208, v72, v73
	v_cvt_pk_bf16_f32 v209, v74, v75
	v_cvt_pk_bf16_f32 v226, v52, v53
	v_cvt_pk_bf16_f32 v227, v54, v55
	v_cvt_pk_bf16_f32 v228, v36, v37
	v_cvt_pk_bf16_f32 v229, v38, v39
	v_add_f32_e32 v76, v250, v251
	s_add_u32 s98, s26, 0xb0000
	s_addc_u32 s99, s27, 0
	global_store_dwordx4 v247, v[206:209], s[98:99]
	global_store_dwordx4 v247, v[226:229], s[98:99] offset:256
	ds_bpermute_b32 v69, v166, v68
	ds_bpermute_b32 v61, v166, v60
	ds_bpermute_b32 v41, v166, v40
	ds_bpermute_b32 v21, v166, v20
	ds_bpermute_b32 v125, v166, v124
	ds_bpermute_b32 v109, v166, v108
	ds_bpermute_b32 v93, v166, v92
	ds_bpermute_b32 v77, v166, v76
	v_cmp_eq_u32_e64 s[42:43], 0, v163
	s_waitcnt lgkmcnt(0)
	v_add_f32_e32 v68, v68, v69
	v_add_f32_e32 v60, v60, v61
	v_add_f32_e32 v40, v40, v41
	v_add_f32_e32 v20, v20, v21
	v_add_f32_e32 v124, v124, v125
	v_add_f32_e32 v108, v108, v109
	v_add_f32_e32 v92, v92, v93
	v_add_f32_e32 v76, v76, v77
	ds_bpermute_b32 v69, v167, v68
	ds_bpermute_b32 v61, v167, v60
	ds_bpermute_b32 v41, v167, v40
	ds_bpermute_b32 v21, v167, v20
	ds_bpermute_b32 v125, v167, v124
	ds_bpermute_b32 v109, v167, v108
	ds_bpermute_b32 v93, v167, v92
	ds_bpermute_b32 v77, v167, v76
	s_waitcnt lgkmcnt(0)
	v_add_f32_e32 v68, v68, v69
	v_add_f32_e32 v60, v60, v61
	v_add_f32_e32 v40, v40, v41
	v_add_f32_e32 v20, v20, v21
	v_add_f32_e32 v124, v124, v125
	v_add_f32_e32 v108, v108, v109
	v_add_f32_e32 v92, v92, v93
	v_add_f32_e32 v76, v76, v77
	s_and_saveexec_b64 s[6:7], s[42:43]
	global_store_dword v255, v68, s[100:101]
	s_add_u32 s98, s100, 0x800
	s_addc_u32 s99, s101, 0
	global_store_dword v255, v60, s[98:99]
	s_add_u32 s98, s100, 0x1000
	s_addc_u32 s99, s101, 0
	global_store_dword v255, v40, s[98:99]
	s_add_u32 s98, s100, 0x1800
	s_addc_u32 s99, s101, 0
	global_store_dword v255, v20, s[98:99]
	s_add_u32 s98, s100, 0x4000
	s_addc_u32 s99, s101, 0
	global_store_dword v255, v124, s[98:99]
	s_add_u32 s98, s100, 0x4800
	s_addc_u32 s99, s101, 0
	global_store_dword v255, v108, s[98:99]
	s_add_u32 s98, s100, 0x5000
	s_addc_u32 s99, s101, 0
	global_store_dword v255, v92, s[98:99]
	s_add_u32 s98, s100, 0x5800
	s_addc_u32 s99, s101, 0
	global_store_dword v255, v76, s[98:99]
	s_or_b64 exec, exec, s[6:7]
.Lres1_done:
	s_ashr_i32 s57, s56, 31
	s_branch .LBB0_654
.LBB0_566:
	s_and_b64 vcc, exec, s[6:7]
	s_cbranch_vccz .LBB0_654
	s_mov_b32 s5, s11
	s_ashr_i32 s55, s54, 31
	v_ashrrev_i32_e32 v145, 31, v144
	s_lshl_b64 s[4:5], s[4:5], 20
	s_waitcnt lgkmcnt(0)
	v_lshl_add_u64 v[36:37], s[54:55], 0, v[144:145]
	s_add_u32 s4, s67, s4
	v_lshlrev_b64 v[36:37], 13, v[36:37]
	s_addc_u32 s5, s68, s5
	v_lshl_add_u64 v[36:37], s[4:5], 0, v[36:37]
	v_lshl_add_u64 v[36:37], v[142:143], 2, v[36:37]
	global_store_dwordx4 v[36:37], v[68:71], off
	global_store_dwordx4 v[36:37], v[64:67], off offset:16
	global_store_dwordx4 v[36:37], v[48:51], off offset:512
	global_store_dwordx4 v[36:37], v[44:47], off offset:528
	s_mov_b64 s[0:1], 0x20000
	v_lshl_add_u64 v[38:39], v[36:37], 0, s[0:1]
	v_add_co_u32_e32 v44, vcc, s70, v36
	s_mov_b64 s[0:1], 0x40000
	s_nop 0
	v_addc_co_u32_e32 v45, vcc, 0, v37, vcc
	global_store_dwordx4 v[44:45], v[60:63], off
	global_store_dwordx4 v[38:39], v[56:59], off offset:16
	global_store_dwordx4 v[38:39], v[28:31], off offset:512
	global_store_dwordx4 v[38:39], v[24:27], off offset:528
	s_nop 1
	v_add_co_u32_e32 v26, vcc, 0x40000, v36
	v_lshl_add_u64 v[24:25], v[36:37], 0, s[0:1]
	s_nop 0
	v_addc_co_u32_e32 v27, vcc, 0, v37, vcc
	global_store_dwordx4 v[26:27], v[40:43], off
	global_store_dwordx4 v[24:25], v[32:35], off offset:16
	global_store_dwordx4 v[24:25], v[12:15], off offset:512
	global_store_dwordx4 v[24:25], v[8:11], off offset:528
	s_mov_b64 s[0:1], 0x60000
	s_nop 0
	v_add_co_u32_e32 v10, vcc, 0x60000, v36
	v_lshl_add_u64 v[8:9], v[36:37], 0, s[0:1]
	s_nop 0
	v_addc_co_u32_e32 v11, vcc, 0, v37, vcc
	global_store_dwordx4 v[10:11], v[20:23], off
	global_store_dwordx4 v[8:9], v[16:19], off offset:16
	global_store_dwordx4 v[8:9], v[4:7], off offset:512
	global_store_dwordx4 v[8:9], v[0:3], off offset:528
	s_andn2_b64 vcc, exec, s[46:47]
	s_mov_b64 s[4:5], -1
	s_cbranch_vccnz .LBB0_549
	s_branch .LBB0_655
.LBB0_654:
	s_andn2_b64 vcc, exec, s[46:47]
	s_mov_b64 s[4:5], -1
	s_cbranch_vccnz .LBB0_549
.LBB0_655:
	s_andn2_b64 vcc, exec, s[24:25]
	s_cbranch_vccnz .LBB0_548
	s_barrier
	s_branch .LBB0_548
.LBB0_658:
	s_waitcnt vmcnt(0)
	v_readlane_b32 s72, v244, 28
	v_readlane_b32 s0, v244, 19
	v_readlane_b32 s73, v244, 29
	v_readlane_b32 s1, v244, 20
	s_movk_i32 s30, 0x2000
	s_movk_i32 s67, 0x1fff
	s_barrier

; __global__ void __launch_bounds__(NTHR, 2) fwd_kernel(Args a) {
;     ...
;               for (int m = MP + gw; m < MREAL; m += NGW) { sample_assemble(XR + (size_t)m * DM, XSP, 11, m - MP, XR + (size_t)m * DM, lane);
;                   row_bf16_ss(XR + (size_t)m * DM, XN + (size_t)m * DM, SSB + (size_t)2 * MPAD + m, lane); }
.LBB0_1016:
	s_or_b64 exec, exec, s[0:1]
	s_ashr_i32 s4, s6, 6
	v_readlane_b32 s0, v245, 26
	s_sub_i32 s0, s0, 0x2000
	s_lshr_b32 s0, s0, 3
	s_lshr_b32 s5, s96, 3
	s_mul_i32 s5, s5, s4
	s_add_i32 s0, s0, s5
	s_addk_i32 s0, 0x2000
	s_cmpk_gt_i32 s0, 0x207f
	s_cbranch_scc1 .LBB0_1021
	v_and_b32_e32 v1, 64, v211
	v_add_u32_e32 v1, 64, v1
	v_xor_b32_e32 v2, 1, v211
	v_cmp_lt_i32_e32 vcc, v2, v1
	s_ashr_i32 s1, s0, 31
	s_lshl_b64 s[6:7], s[0:1], 2
	v_cndmask_b32_e32 v2, v211, v2, vcc
	v_lshlrev_b32_e32 v62, 2, v2
	v_xor_b32_e32 v2, 2, v211
	v_cmp_lt_i32_e32 vcc, v2, v1
	s_add_u32 s6, s6, 0x221f8800
	v_and_b32_e32 v0, 63, v6
	v_cndmask_b32_e32 v2, v211, v2, vcc
	v_lshlrev_b32_e32 v63, 2, v2
	v_xor_b32_e32 v2, 4, v211
	v_cmp_lt_i32_e32 vcc, v2, v1
	s_addc_u32 s7, s7, 0
	s_lshl_b64 s[8:9], s[0:1], 12
	v_cndmask_b32_e32 v2, v211, v2, vcc
	v_lshlrev_b32_e32 v64, 2, v2
	v_xor_b32_e32 v2, 8, v211
	v_cmp_lt_i32_e32 vcc, v2, v1
	s_load_dwordx2 s[2:3], s[2:3], 0x98
	v_lshl_or_b32 v32, v0, 3, s8
	v_cndmask_b32_e32 v2, v211, v2, vcc
	v_lshlrev_b32_e32 v65, 2, v2
	v_xor_b32_e32 v2, 16, v211
	v_cmp_lt_i32_e32 vcc, v2, v1
	v_mov_b32_e32 v33, s9
	s_lshl_b64 s[8:9], s[0:1], 13
	v_cndmask_b32_e32 v2, v211, v2, vcc
	v_readlane_b32 s1, v246, 4
	v_lshlrev_b32_e32 v66, 2, v2
	v_xor_b32_e32 v2, 32, v211
	s_add_i32 s4, s0, 0xffffe000
	v_cmp_lt_i32_e32 vcc, v2, v1
	s_ashr_i32 s5, s4, 31
	v_cmp_eq_u32_e64 s[40:41], 0, v0
	v_cndmask_b32_e32 v1, v211, v2, vcc
	v_lshlrev_b32_e32 v0, 4, v0
	s_lshl_b64 s[4:5], s[4:5], 13
	v_lshlrev_b32_e32 v67, 2, v1
	v_or_b32_e32 v34, s8, v0
	v_mov_b32_e32 v35, s9
	v_or_b32_e32 v36, s4, v0
	v_mov_b32_e32 v37, s5
	s_branch .LBB0_1019

; __device__ __forceinline__ void sample_assemble(const float* base, const float* XSP, int nsp, int s, float* xr, int lane) {
;     const f32x4* br = (const f32x4*)base + lane; f32x4* o = (f32x4*)xr + lane;
; #pragma unroll
;     for (int j = 0; j < 8; ++j) { f32x4 v = br[64 * j];
;         for (int sp = 0; sp < nsp; ++sp) v += *((const f32x4*)(XSP + ((size_t)sp * NS + s) * DM) + lane + 64 * j);
;         o[64 * j] = v; }
; }
.LBB0_1019:
	s_waitcnt lgkmcnt(0)
	v_readfirstlane_b32 s98, v36
	v_readfirstlane_b32 s99, v37
	v_readfirstlane_b32 s100, v34
	v_readfirstlane_b32 s101, v35
	v_lshlrev_b32_e32 v39, 4, v211
	s_add_u32 s98, s98, s2
	s_addc_u32 s99, s99, s3
	s_add_u32 s98, s98, 0x216e4000
	s_addc_u32 s99, s99, 0
	s_add_u32 s100, s100, s2
	s_addc_u32 s101, s101, s3
	s_add_u32 s100, s100, 0xe700000
	s_addc_u32 s101, s101, 0
	v_add_u32_e32 v0, 0x1000, v39
	global_load_dwordx4 v[46:49], v39, s[100:101]
	global_load_dwordx4 v[50:53], v39, s[98:99]
	s_add_u32 s4, s98, 0x100000
	s_addc_u32 s5, s99, 0
	global_load_dwordx4 v[54:57], v39, s[4:5]
	s_add_u32 s4, s98, 0x200000
	s_addc_u32 s5, s99, 0
	global_load_dwordx4 v[58:61], v39, s[4:5]
	s_add_u32 s4, s98, 0x300000
	s_addc_u32 s5, s99, 0
	global_load_dwordx4 v[78:81], v39, s[4:5]
	s_add_u32 s4, s98, 0x400000
	s_addc_u32 s5, s99, 0
	global_load_dwordx4 v[82:85], v39, s[4:5]
	s_add_u32 s4, s98, 0x500000
	s_addc_u32 s5, s99, 0
	global_load_dwordx4 v[86:89], v39, s[4:5]
	s_add_u32 s4, s98, 0x600000
	s_addc_u32 s5, s99, 0
	global_load_dwordx4 v[90:93], v39, s[4:5]
	s_add_u32 s4, s98, 0x700000
	s_addc_u32 s5, s99, 0
	global_load_dwordx4 v[94:97], v39, s[4:5]
	s_add_u32 s4, s98, 0x800000
	s_addc_u32 s5, s99, 0
	global_load_dwordx4 v[98:101], v39, s[4:5]
	s_add_u32 s4, s98, 0x900000
	s_addc_u32 s5, s99, 0
	global_load_dwordx4 v[102:105], v39, s[4:5]
	s_add_u32 s4, s98, 0xa00000
	s_addc_u32 s5, s99, 0
	global_load_dwordx4 v[128:131], v39, s[4:5]
	global_load_dwordx4 v[132:135], v39, s[100:101] offset:1024
	global_load_dwordx4 v[136:139], v39, s[98:99] offset:1024
	s_add_u32 s4, s98, 0x100000
	s_addc_u32 s5, s99, 0
	global_load_dwordx4 v[140:143], v39, s[4:5] offset:1024
	s_add_u32 s4, s98, 0x200000
	s_addc_u32 s5, s99, 0
	global_load_dwordx4 v[144:147], v39, s[4:5] offset:1024
	s_add_u32 s4, s98, 0x300000
	s_addc_u32 s5, s99, 0
	global_load_dwordx4 v[148:151], v39, s[4:5] offset:1024
	s_add_u32 s4, s98, 0x400000
	s_addc_u32 s5, s99, 0
	global_load_dwordx4 v[152:155], v39, s[4:5] offset:1024
	s_add_u32 s4, s98, 0x500000
	s_addc_u32 s5, s99, 0
	global_load_dwordx4 v[156:159], v39, s[4:5] offset:1024
	s_add_u32 s4, s98, 0x600000
	s_addc_u32 s5, s99, 0
	global_load_dwordx4 v[160:163], v39, s[4:5] offset:1024
	s_add_u32 s4, s98, 0x700000
	s_addc_u32 s5, s99, 0
	global_load_dwordx4 v[164:167], v39, s[4:5] offset:1024
	s_add_u32 s4, s98, 0x800000
	s_addc_u32 s5, s99, 0
	global_load_dwordx4 v[178:181], v39, s[4:5] offset:1024
	s_add_u32 s4, s98, 0x900000
	s_addc_u32 s5, s99, 0
	global_load_dwordx4 v[182:185], v39, s[4:5] offset:1024
	s_add_u32 s4, s98, 0xa00000
	s_addc_u32 s5, s99, 0
	global_load_dwordx4 v[186:189], v39, s[4:5] offset:1024
	s_waitcnt vmcnt(12)
	v_pk_add_f32 v[2:3], v[46:47], v[50:51]
	v_pk_add_f32 v[4:5], v[48:49], v[52:53]
	v_pk_add_f32 v[2:3], v[2:3], v[54:55]
	v_pk_add_f32 v[4:5], v[4:5], v[56:57]
	v_pk_add_f32 v[2:3], v[2:3], v[58:59]
	v_pk_add_f32 v[4:5], v[4:5], v[60:61]
	v_pk_add_f32 v[2:3], v[2:3], v[78:79]
	v_pk_add_f32 v[4:5], v[4:5], v[80:81]
	v_pk_add_f32 v[2:3], v[2:3], v[82:83]
	v_pk_add_f32 v[4:5], v[4:5], v[84:85]
	v_pk_add_f32 v[2:3], v[2:3], v[86:87]
	v_pk_add_f32 v[4:5], v[4:5], v[88:89]
	v_pk_add_f32 v[2:3], v[2:3], v[90:91]
	v_pk_add_f32 v[4:5], v[4:5], v[92:93]
	v_pk_add_f32 v[2:3], v[2:3], v[94:95]
	v_pk_add_f32 v[4:5], v[4:5], v[96:97]
	v_pk_add_f32 v[2:3], v[2:3], v[98:99]
	v_pk_add_f32 v[4:5], v[4:5], v[100:101]
	v_pk_add_f32 v[2:3], v[2:3], v[102:103]
	v_pk_add_f32 v[4:5], v[4:5], v[104:105]
	v_pk_add_f32 v[2:3], v[2:3], v[128:129]
	v_pk_add_f32 v[4:5], v[4:5], v[130:131]
	global_store_dwordx4 v39, v[2:5], s[100:101]
	global_load_dwordx4 v[46:49], v39, s[100:101] offset:2048
	global_load_dwordx4 v[50:53], v39, s[98:99] offset:2048
	s_add_u32 s4, s98, 0x100000
	s_addc_u32 s5, s99, 0
	global_load_dwordx4 v[54:57], v39, s[4:5] offset:2048
	s_add_u32 s4, s98, 0x200000
	s_addc_u32 s5, s99, 0
	global_load_dwordx4 v[58:61], v39, s[4:5] offset:2048
	s_add_u32 s4, s98, 0x300000
	s_addc_u32 s5, s99, 0
	global_load_dwordx4 v[78:81], v39, s[4:5] offset:2048
	s_add_u32 s4, s98, 0x400000
	s_addc_u32 s5, s99, 0
	global_load_dwordx4 v[82:85], v39, s[4:5] offset:2048
	s_add_u32 s4, s98, 0x500000
	s_addc_u32 s5, s99, 0
	global_load_dwordx4 v[86:89], v39, s[4:5] offset:2048
	s_add_u32 s4, s98, 0x600000
	s_addc_u32 s5, s99, 0
	global_load_dwordx4 v[90:93], v39, s[4:5] offset:2048
	s_add_u32 s4, s98, 0x700000
	s_addc_u32 s5, s99, 0
	global_load_dwordx4 v[94:97], v39, s[4:5] offset:2048
	s_add_u32 s4, s98, 0x800000
	s_addc_u32 s5, s99, 0
	global_load_dwordx4 v[98:101], v39, s[4:5] offset:2048
	s_add_u32 s4, s98, 0x900000
	s_addc_u32 s5, s99, 0
	global_load_dwordx4 v[102:105], v39, s[4:5] offset:2048
	s_add_u32 s4, s98, 0xa00000
	s_addc_u32 s5, s99, 0
	global_load_dwordx4 v[128:131], v39, s[4:5] offset:2048
	s_waitcnt vmcnt(13)
; __device__ __forceinline__ void sample_assemble(const float* base, const float* XSP, int nsp, int s, float* xr, int lane) {
;     const f32x4* br = (const f32x4*)base + lane; f32x4* o = (f32x4*)xr + lane;
; #pragma unroll
;     for (int j = 0; j < 8; ++j) { f32x4 v = br[64 * j];
;         for (int sp = 0; sp < nsp; ++sp) v += *((const f32x4*)(XSP + ((size_t)sp * NS + s) * DM) + lane + 64 * j);
;         o[64 * j] = v; }
; }
	v_pk_add_f32 v[6:7], v[132:133], v[136:137]
	v_pk_add_f32 v[8:9], v[134:135], v[138:139]
	v_pk_add_f32 v[6:7], v[6:7], v[140:141]
	v_pk_add_f32 v[8:9], v[8:9], v[142:143]
	v_pk_add_f32 v[6:7], v[6:7], v[144:145]
	v_pk_add_f32 v[8:9], v[8:9], v[146:147]
	v_pk_add_f32 v[6:7], v[6:7], v[148:149]
	v_pk_add_f32 v[8:9], v[8:9], v[150:151]
	v_pk_add_f32 v[6:7], v[6:7], v[152:153]
	v_pk_add_f32 v[8:9], v[8:9], v[154:155]
	v_pk_add_f32 v[6:7], v[6:7], v[156:157]
	v_pk_add_f32 v[8:9], v[8:9], v[158:159]
	v_pk_add_f32 v[6:7], v[6:7], v[160:161]
	v_pk_add_f32 v[8:9], v[8:9], v[162:163]
	v_pk_add_f32 v[6:7], v[6:7], v[164:165]
	v_pk_add_f32 v[8:9], v[8:9], v[166:167]
	v_pk_add_f32 v[6:7], v[6:7], v[178:179]
	v_pk_add_f32 v[8:9], v[8:9], v[180:181]
	v_pk_add_f32 v[6:7], v[6:7], v[182:183]
	v_pk_add_f32 v[8:9], v[8:9], v[184:185]
	v_pk_add_f32 v[6:7], v[6:7], v[186:187]
	v_pk_add_f32 v[8:9], v[8:9], v[188:189]
	global_store_dwordx4 v39, v[6:9], s[100:101] offset:1024
	global_load_dwordx4 v[132:135], v39, s[100:101] offset:3072
	global_load_dwordx4 v[136:139], v39, s[98:99] offset:3072
	s_add_u32 s4, s98, 0x100000
	s_addc_u32 s5, s99, 0
	global_load_dwordx4 v[140:143], v39, s[4:5] offset:3072
	s_add_u32 s4, s98, 0x200000
	s_addc_u32 s5, s99, 0
	global_load_dwordx4 v[144:147], v39, s[4:5] offset:3072
	s_add_u32 s4, s98, 0x300000
	s_addc_u32 s5, s99, 0
	global_load_dwordx4 v[148:151], v39, s[4:5] offset:3072
	s_add_u32 s4, s98, 0x400000
	s_addc_u32 s5, s99, 0
	global_load_dwordx4 v[152:155], v39, s[4:5] offset:3072
	s_add_u32 s4, s98, 0x500000
	s_addc_u32 s5, s99, 0
	global_load_dwordx4 v[156:159], v39, s[4:5] offset:3072
	s_add_u32 s4, s98, 0x600000
	s_addc_u32 s5, s99, 0
	global_load_dwordx4 v[160:163], v39, s[4:5] offset:3072
	s_add_u32 s4, s98, 0x700000
	s_addc_u32 s5, s99, 0
	global_load_dwordx4 v[164:167], v39, s[4:5] offset:3072
	s_add_u32 s4, s98, 0x800000
	s_addc_u32 s5, s99, 0
	global_load_dwordx4 v[178:181], v39, s[4:5] offset:3072
	s_add_u32 s4, s98, 0x900000
	s_addc_u32 s5, s99, 0
	global_load_dwordx4 v[182:185], v39, s[4:5] offset:3072
	s_add_u32 s4, s98, 0xa00000
	s_addc_u32 s5, s99, 0
	global_load_dwordx4 v[186:189], v39, s[4:5] offset:3072
	s_waitcnt vmcnt(13)
	v_pk_add_f32 v[10:11], v[46:47], v[50:51]
	v_pk_add_f32 v[12:13], v[48:49], v[52:53]
	v_pk_add_f32 v[10:11], v[10:11], v[54:55]
	v_pk_add_f32 v[12:13], v[12:13], v[56:57]
	v_pk_add_f32 v[10:11], v[10:11], v[58:59]
	v_pk_add_f32 v[12:13], v[12:13], v[60:61]
	v_pk_add_f32 v[10:11], v[10:11], v[78:79]
	v_pk_add_f32 v[12:13], v[12:13], v[80:81]
	v_pk_add_f32 v[10:11], v[10:11], v[82:83]
	v_pk_add_f32 v[12:13], v[12:13], v[84:85]
	v_pk_add_f32 v[10:11], v[10:11], v[86:87]
	v_pk_add_f32 v[12:13], v[12:13], v[88:89]
	v_pk_add_f32 v[10:11], v[10:11], v[90:91]
	v_pk_add_f32 v[12:13], v[12:13], v[92:93]
	v_pk_add_f32 v[10:11], v[10:11], v[94:95]
	v_pk_add_f32 v[12:13], v[12:13], v[96:97]
	v_pk_add_f32 v[10:11], v[10:11], v[98:99]
	v_pk_add_f32 v[12:13], v[12:13], v[100:101]
	v_pk_add_f32 v[10:11], v[10:11], v[102:103]
	v_pk_add_f32 v[12:13], v[12:13], v[104:105]
	v_pk_add_f32 v[10:11], v[10:11], v[128:129]
	v_pk_add_f32 v[12:13], v[12:13], v[130:131]
	global_store_dwordx4 v39, v[10:13], s[100:101] offset:2048
	global_load_dwordx4 v[46:49], v0, s[100:101]
	global_load_dwordx4 v[50:53], v0, s[98:99]
	s_add_u32 s4, s98, 0x100000
	s_addc_u32 s5, s99, 0
	global_load_dwordx4 v[54:57], v0, s[4:5]
	s_add_u32 s4, s98, 0x200000
	s_addc_u32 s5, s99, 0
	global_load_dwordx4 v[58:61], v0, s[4:5]
	s_add_u32 s4, s98, 0x300000
	s_addc_u32 s5, s99, 0
	global_load_dwordx4 v[78:81], v0, s[4:5]
	s_add_u32 s4, s98, 0x400000
	s_addc_u32 s5, s99, 0
	global_load_dwordx4 v[82:85], v0, s[4:5]
	s_add_u32 s4, s98, 0x500000
	s_addc_u32 s5, s99, 0
	global_load_dwordx4 v[86:89], v0, s[4:5]
	s_add_u32 s4, s98, 0x600000
	s_addc_u32 s5, s99, 0
	global_load_dwordx4 v[90:93], v0, s[4:5]
	s_add_u32 s4, s98, 0x700000
	s_addc_u32 s5, s99, 0
	global_load_dwordx4 v[94:97], v0, s[4:5]
	s_add_u32 s4, s98, 0x800000
	s_addc_u32 s5, s99, 0
	global_load_dwordx4 v[98:101], v0, s[4:5]
	s_add_u32 s4, s98, 0x900000
	s_addc_u32 s5, s99, 0
	global_load_dwordx4 v[102:105], v0, s[4:5]
	s_add_u32 s4, s98, 0xa00000
	s_addc_u32 s5, s99, 0
	global_load_dwordx4 v[128:131], v0, s[4:5]
	s_waitcnt vmcnt(13)
	v_pk_add_f32 v[14:15], v[132:133], v[136:137]
	v_pk_add_f32 v[16:17], v[134:135], v[138:139]
	v_pk_add_f32 v[14:15], v[14:15], v[140:141]
	v_pk_add_f32 v[16:17], v[16:17], v[142:143]
	v_pk_add_f32 v[14:15], v[14:15], v[144:145]
	v_pk_add_f32 v[16:17], v[16:17], v[146:147]
	v_pk_add_f32 v[14:15], v[14:15], v[148:149]
	v_pk_add_f32 v[16:17], v[16:17], v[150:151]
	v_pk_add_f32 v[14:15], v[14:15], v[152:153]
	v_pk_add_f32 v[16:17], v[16:17], v[154:155]
	v_pk_add_f32 v[14:15], v[14:15], v[156:157]
	v_pk_add_f32 v[16:17], v[16:17], v[158:159]
	v_pk_add_f32 v[14:15], v[14:15], v[160:161]
	v_pk_add_f32 v[16:17], v[16:17], v[162:163]
	v_pk_add_f32 v[14:15], v[14:15], v[164:165]
	v_pk_add_f32 v[16:17], v[16:17], v[166:167]
	v_pk_add_f32 v[14:15], v[14:15], v[178:179]
	v_pk_add_f32 v[16:17], v[16:17], v[180:181]
	v_pk_add_f32 v[14:15], v[14:15], v[182:183]
	v_pk_add_f32 v[16:17], v[16:17], v[184:185]
	v_pk_add_f32 v[14:15], v[14:15], v[186:187]
	v_pk_add_f32 v[16:17], v[16:17], v[188:189]
	global_store_dwordx4 v39, v[14:17], s[100:101] offset:3072
	global_load_dwordx4 v[132:135], v0, s[100:101] offset:1024
	global_load_dwordx4 v[136:139], v0, s[98:99] offset:1024
	s_add_u32 s4, s98, 0x100000
	s_addc_u32 s5, s99, 0
	global_load_dwordx4 v[140:143], v0, s[4:5] offset:1024
	s_add_u32 s4, s98, 0x200000
	s_addc_u32 s5, s99, 0
	global_load_dwordx4 v[144:147], v0, s[4:5] offset:1024
	s_add_u32 s4, s98, 0x300000
	s_addc_u32 s5, s99, 0
	global_load_dwordx4 v[148:151], v0, s[4:5] offset:1024
	s_add_u32 s4, s98, 0x400000
	s_addc_u32 s5, s99, 0
	global_load_dwordx4 v[152:155], v0, s[4:5] offset:1024
	s_add_u32 s4, s98, 0x500000
	s_addc_u32 s5, s99, 0
	global_load_dwordx4 v[156:159], v0, s[4:5] offset:1024
	s_add_u32 s4, s98, 0x600000
	s_addc_u32 s5, s99, 0
	global_load_dwordx4 v[160:163], v0, s[4:5] offset:1024
	s_add_u32 s4, s98, 0x700000
	s_addc_u32 s5, s99, 0
	global_load_dwordx4 v[164:167], v0, s[4:5] offset:1024
	s_add_u32 s4, s98, 0x800000
	s_addc_u32 s5, s99, 0
	global_load_dwordx4 v[178:181], v0, s[4:5] offset:1024
	s_add_u32 s4, s98, 0x900000
	s_addc_u32 s5, s99, 0
	global_load_dwordx4 v[182:185], v0, s[4:5] offset:1024
	s_add_u32 s4, s98, 0xa00000
	s_addc_u32 s5, s99, 0
	global_load_dwordx4 v[186:189], v0, s[4:5] offset:1024
	s_waitcnt vmcnt(13)
; __device__ __forceinline__ void sample_assemble(const float* base, const float* XSP, int nsp, int s, float* xr, int lane) {
;     const f32x4* br = (const f32x4*)base + lane; f32x4* o = (f32x4*)xr + lane;
; #pragma unroll
;     for (int j = 0; j < 8; ++j) { f32x4 v = br[64 * j];
;         for (int sp = 0; sp < nsp; ++sp) v += *((const f32x4*)(XSP + ((size_t)sp * NS + s) * DM) + lane + 64 * j);
;         o[64 * j] = v; }
; }
	v_pk_add_f32 v[18:19], v[46:47], v[50:51]
	v_pk_add_f32 v[20:21], v[48:49], v[52:53]
	v_pk_add_f32 v[18:19], v[18:19], v[54:55]
	v_pk_add_f32 v[20:21], v[20:21], v[56:57]
	v_pk_add_f32 v[18:19], v[18:19], v[58:59]
	v_pk_add_f32 v[20:21], v[20:21], v[60:61]
	v_pk_add_f32 v[18:19], v[18:19], v[78:79]
	v_pk_add_f32 v[20:21], v[20:21], v[80:81]
	v_pk_add_f32 v[18:19], v[18:19], v[82:83]
	v_pk_add_f32 v[20:21], v[20:21], v[84:85]
	v_pk_add_f32 v[18:19], v[18:19], v[86:87]
	v_pk_add_f32 v[20:21], v[20:21], v[88:89]
	v_pk_add_f32 v[18:19], v[18:19], v[90:91]
	v_pk_add_f32 v[20:21], v[20:21], v[92:93]
	v_pk_add_f32 v[18:19], v[18:19], v[94:95]
	v_pk_add_f32 v[20:21], v[20:21], v[96:97]
	v_pk_add_f32 v[18:19], v[18:19], v[98:99]
	v_pk_add_f32 v[20:21], v[20:21], v[100:101]
	v_pk_add_f32 v[18:19], v[18:19], v[102:103]
	v_pk_add_f32 v[20:21], v[20:21], v[104:105]
	v_pk_add_f32 v[18:19], v[18:19], v[128:129]
	v_pk_add_f32 v[20:21], v[20:21], v[130:131]
	global_store_dwordx4 v0, v[18:21], s[100:101]
	global_load_dwordx4 v[46:49], v0, s[100:101] offset:2048
	global_load_dwordx4 v[50:53], v0, s[98:99] offset:2048
	s_add_u32 s4, s98, 0x100000
	s_addc_u32 s5, s99, 0
	global_load_dwordx4 v[54:57], v0, s[4:5] offset:2048
	s_add_u32 s4, s98, 0x200000
	s_addc_u32 s5, s99, 0
	global_load_dwordx4 v[58:61], v0, s[4:5] offset:2048
	s_add_u32 s4, s98, 0x300000
	s_addc_u32 s5, s99, 0
	global_load_dwordx4 v[78:81], v0, s[4:5] offset:2048
	s_add_u32 s4, s98, 0x400000
	s_addc_u32 s5, s99, 0
	global_load_dwordx4 v[82:85], v0, s[4:5] offset:2048
	s_add_u32 s4, s98, 0x500000
	s_addc_u32 s5, s99, 0
	global_load_dwordx4 v[86:89], v0, s[4:5] offset:2048
	s_add_u32 s4, s98, 0x600000
	s_addc_u32 s5, s99, 0
	global_load_dwordx4 v[90:93], v0, s[4:5] offset:2048
	s_add_u32 s4, s98, 0x700000
	s_addc_u32 s5, s99, 0
	global_load_dwordx4 v[94:97], v0, s[4:5] offset:2048
	s_add_u32 s4, s98, 0x800000
	s_addc_u32 s5, s99, 0
	global_load_dwordx4 v[98:101], v0, s[4:5] offset:2048
	s_add_u32 s4, s98, 0x900000
	s_addc_u32 s5, s99, 0
	global_load_dwordx4 v[102:105], v0, s[4:5] offset:2048
	s_add_u32 s4, s98, 0xa00000
	s_addc_u32 s5, s99, 0
	global_load_dwordx4 v[128:131], v0, s[4:5] offset:2048
	s_waitcnt vmcnt(13)
	v_pk_add_f32 v[22:23], v[132:133], v[136:137]
	v_pk_add_f32 v[24:25], v[134:135], v[138:139]
	v_pk_add_f32 v[22:23], v[22:23], v[140:141]
	v_pk_add_f32 v[24:25], v[24:25], v[142:143]
	v_pk_add_f32 v[22:23], v[22:23], v[144:145]
	v_pk_add_f32 v[24:25], v[24:25], v[146:147]
	v_pk_add_f32 v[22:23], v[22:23], v[148:149]
	v_pk_add_f32 v[24:25], v[24:25], v[150:151]
	v_pk_add_f32 v[22:23], v[22:23], v[152:153]
	v_pk_add_f32 v[24:25], v[24:25], v[154:155]
	v_pk_add_f32 v[22:23], v[22:23], v[156:157]
	v_pk_add_f32 v[24:25], v[24:25], v[158:159]
	v_pk_add_f32 v[22:23], v[22:23], v[160:161]
	v_pk_add_f32 v[24:25], v[24:25], v[162:163]
	v_pk_add_f32 v[22:23], v[22:23], v[164:165]
	v_pk_add_f32 v[24:25], v[24:25], v[166:167]
	v_pk_add_f32 v[22:23], v[22:23], v[178:179]
	v_pk_add_f32 v[24:25], v[24:25], v[180:181]
	v_pk_add_f32 v[22:23], v[22:23], v[182:183]
	v_pk_add_f32 v[24:25], v[24:25], v[184:185]
	v_pk_add_f32 v[22:23], v[22:23], v[186:187]
	v_pk_add_f32 v[24:25], v[24:25], v[188:189]
	global_store_dwordx4 v0, v[22:25], s[100:101] offset:1024
	global_load_dwordx4 v[132:135], v0, s[100:101] offset:3072
	global_load_dwordx4 v[136:139], v0, s[98:99] offset:3072
	s_add_u32 s4, s98, 0x100000
	s_addc_u32 s5, s99, 0
	global_load_dwordx4 v[140:143], v0, s[4:5] offset:3072
	s_add_u32 s4, s98, 0x200000
	s_addc_u32 s5, s99, 0
	global_load_dwordx4 v[144:147], v0, s[4:5] offset:3072
	s_add_u32 s4, s98, 0x300000
	s_addc_u32 s5, s99, 0
	global_load_dwordx4 v[148:151], v0, s[4:5] offset:3072
	s_add_u32 s4, s98, 0x400000
	s_addc_u32 s5, s99, 0
	global_load_dwordx4 v[152:155], v0, s[4:5] offset:3072
	s_add_u32 s4, s98, 0x500000
	s_addc_u32 s5, s99, 0
	global_load_dwordx4 v[156:159], v0, s[4:5] offset:3072
	s_add_u32 s4, s98, 0x600000
	s_addc_u32 s5, s99, 0
	global_load_dwordx4 v[160:163], v0, s[4:5] offset:3072
	s_add_u32 s4, s98, 0x700000
	s_addc_u32 s5, s99, 0
	global_load_dwordx4 v[164:167], v0, s[4:5] offset:3072
	s_add_u32 s4, s98, 0x800000
	s_addc_u32 s5, s99, 0
	global_load_dwordx4 v[178:181], v0, s[4:5] offset:3072
	s_add_u32 s4, s98, 0x900000
	s_addc_u32 s5, s99, 0
	global_load_dwordx4 v[182:185], v0, s[4:5] offset:3072
	s_add_u32 s4, s98, 0xa00000
	s_addc_u32 s5, s99, 0
	global_load_dwordx4 v[186:189], v0, s[4:5] offset:3072
	s_waitcnt vmcnt(13)
; __device__ __forceinline__ unsigned cvt_pk_bf16(float lo, float hi) { unsigned r; asm volatile("v_cvt_pk_bf16_f32 %0, %1, %2" : "=v"(r) : "v"(lo), "v"(hi)); return r; }
; __device__ __forceinline__ void row_bf16_ss(const float* xrow, bf16_t* orow, float* ss, int lane) {
;     const f32x4* xr = (const f32x4*)xrow + lane; f32x4 v[8]; float s = 0.f;
; #pragma unroll
;     for (int j = 0; j < 8; ++j) { v[j] = xr[64 * j]; s += (v[j].x * v[j].x + v[j].y * v[j].y) + (v[j].z * v[j].z + v[j].w * v[j].w); }
;     s = wave_sum(s); u32x2* o8 = (u32x2*)orow + lane;
; #pragma unroll
;     for (int j = 0; j < 8; ++j) { u32x2 w; w.x = cvt_pk_bf16(v[j].x, v[j].y); w.y = cvt_pk_bf16(v[j].z, v[j].w); o8[64 * j] = w; }
;     if (lane == 0) *ss = s;
; }
; __device__ __forceinline__ void sample_assemble(const float* base, const float* XSP, int nsp, int s, float* xr, int lane) {
;     const f32x4* br = (const f32x4*)base + lane; f32x4* o = (f32x4*)xr + lane;
; #pragma unroll
;     for (int j = 0; j < 8; ++j) { f32x4 v = br[64 * j];
;         for (int sp = 0; sp < nsp; ++sp) v += *((const f32x4*)(XSP + ((size_t)sp * NS + s) * DM) + lane + 64 * j);
;         o[64 * j] = v; }
; }
	v_pk_add_f32 v[26:27], v[46:47], v[50:51]
	v_pk_add_f32 v[28:29], v[48:49], v[52:53]
	v_pk_add_f32 v[26:27], v[26:27], v[54:55]
	v_pk_add_f32 v[28:29], v[28:29], v[56:57]
	v_pk_add_f32 v[26:27], v[26:27], v[58:59]
	v_pk_add_f32 v[28:29], v[28:29], v[60:61]
	v_pk_add_f32 v[26:27], v[26:27], v[78:79]
	v_pk_add_f32 v[28:29], v[28:29], v[80:81]
	v_pk_add_f32 v[26:27], v[26:27], v[82:83]
	v_pk_add_f32 v[28:29], v[28:29], v[84:85]
	v_pk_add_f32 v[26:27], v[26:27], v[86:87]
	v_pk_add_f32 v[28:29], v[28:29], v[88:89]
	v_pk_add_f32 v[26:27], v[26:27], v[90:91]
	v_pk_add_f32 v[28:29], v[28:29], v[92:93]
	v_pk_add_f32 v[26:27], v[26:27], v[94:95]
	v_pk_add_f32 v[28:29], v[28:29], v[96:97]
	v_pk_add_f32 v[26:27], v[26:27], v[98:99]
	v_pk_add_f32 v[28:29], v[28:29], v[100:101]
	v_pk_add_f32 v[26:27], v[26:27], v[102:103]
	v_pk_add_f32 v[28:29], v[28:29], v[104:105]
	v_pk_add_f32 v[26:27], v[26:27], v[128:129]
	v_pk_add_f32 v[28:29], v[28:29], v[130:131]
	global_store_dwordx4 v0, v[26:29], s[100:101] offset:2048
	s_waitcnt vmcnt(1)
	v_pk_add_f32 v[42:43], v[132:133], v[136:137]
	v_pk_add_f32 v[44:45], v[134:135], v[138:139]
	v_pk_add_f32 v[42:43], v[42:43], v[140:141]
	v_pk_add_f32 v[44:45], v[44:45], v[142:143]
	v_pk_add_f32 v[42:43], v[42:43], v[144:145]
	v_pk_add_f32 v[44:45], v[44:45], v[146:147]
	v_pk_add_f32 v[42:43], v[42:43], v[148:149]
	v_pk_add_f32 v[44:45], v[44:45], v[150:151]
	v_pk_add_f32 v[42:43], v[42:43], v[152:153]
	v_pk_add_f32 v[44:45], v[44:45], v[154:155]
	v_pk_add_f32 v[42:43], v[42:43], v[156:157]
	v_pk_add_f32 v[44:45], v[44:45], v[158:159]
	v_pk_add_f32 v[42:43], v[42:43], v[160:161]
	v_pk_add_f32 v[44:45], v[44:45], v[162:163]
	v_pk_add_f32 v[42:43], v[42:43], v[164:165]
	v_pk_add_f32 v[44:45], v[44:45], v[166:167]
	v_pk_add_f32 v[42:43], v[42:43], v[178:179]
	v_pk_add_f32 v[44:45], v[44:45], v[180:181]
	v_pk_add_f32 v[42:43], v[42:43], v[182:183]
	v_pk_add_f32 v[44:45], v[44:45], v[184:185]
	v_pk_add_f32 v[42:43], v[42:43], v[186:187]
	v_pk_add_f32 v[44:45], v[44:45], v[188:189]
	global_store_dwordx4 v0, v[42:45], s[100:101] offset:3072
	v_mul_f32_e32 v40, v3, v3
	v_mul_f32_e32 v30, v5, v5
	v_fmac_f32_e32 v40, v2, v2
	v_fmac_f32_e32 v30, v4, v4
	v_add_f32_e32 v40, v40, v30
	v_mul_f32_e32 v1, v7, v7
	v_mul_f32_e32 v30, v9, v9
	v_fmac_f32_e32 v1, v6, v6
	v_fmac_f32_e32 v30, v8, v8
	v_add_f32_e32 v1, v1, v30
	v_add_f32_e32 v40, v40, v1
	v_mul_f32_e32 v1, v11, v11
	v_mul_f32_e32 v30, v13, v13
	v_fmac_f32_e32 v1, v10, v10
	v_fmac_f32_e32 v30, v12, v12
	v_add_f32_e32 v1, v1, v30
	v_add_f32_e32 v40, v40, v1
	v_mul_f32_e32 v1, v15, v15
	v_mul_f32_e32 v30, v17, v17
	v_fmac_f32_e32 v1, v14, v14
	v_fmac_f32_e32 v30, v16, v16
	v_add_f32_e32 v1, v1, v30
	v_add_f32_e32 v40, v40, v1
	v_mul_f32_e32 v1, v19, v19
	v_mul_f32_e32 v30, v21, v21
	v_fmac_f32_e32 v1, v18, v18
	v_fmac_f32_e32 v30, v20, v20
	v_add_f32_e32 v1, v1, v30
	v_add_f32_e32 v40, v40, v1
	v_mul_f32_e32 v1, v23, v23
	v_mul_f32_e32 v30, v25, v25
	v_fmac_f32_e32 v1, v22, v22
	v_fmac_f32_e32 v30, v24, v24
	v_add_f32_e32 v1, v1, v30
	v_add_f32_e32 v40, v40, v1
	v_mul_f32_e32 v1, v27, v27
	v_mul_f32_e32 v30, v29, v29
	v_fmac_f32_e32 v1, v26, v26
	v_fmac_f32_e32 v30, v28, v28
	v_add_f32_e32 v1, v1, v30
	v_add_f32_e32 v40, v40, v1
	v_mul_f32_e32 v1, v43, v43
	v_mul_f32_e32 v30, v45, v45
	v_fmac_f32_e32 v1, v42, v42
	v_fmac_f32_e32 v30, v44, v44
	v_add_f32_e32 v1, v1, v30
	v_add_f32_e32 v40, v40, v1
	v_lshlrev_b32_e32 v38, 3, v211
	v_readfirstlane_b32 s4, v32
	v_readfirstlane_b32 s5, v33
	s_add_u32 s4, s4, s2
	s_addc_u32 s5, s5, s3
	s_add_u32 s4, s4, 0xc600000
	s_addc_u32 s5, s5, 0
	v_cvt_pk_bf16_f32 v106, v2, v3
	v_cvt_pk_bf16_f32 v107, v4, v5
	global_store_dwordx2 v38, v[106:107], s[4:5]
	v_cvt_pk_bf16_f32 v190, v6, v7
	v_cvt_pk_bf16_f32 v191, v8, v9
	global_store_dwordx2 v38, v[190:191], s[4:5] offset:512
	v_cvt_pk_bf16_f32 v192, v10, v11
	v_cvt_pk_bf16_f32 v193, v12, v13
	global_store_dwordx2 v38, v[192:193], s[4:5] offset:1024
	v_cvt_pk_bf16_f32 v194, v14, v15
	v_cvt_pk_bf16_f32 v195, v16, v17
	global_store_dwordx2 v38, v[194:195], s[4:5] offset:1536
	v_cvt_pk_bf16_f32 v196, v18, v19
	v_cvt_pk_bf16_f32 v197, v20, v21
	global_store_dwordx2 v38, v[196:197], s[4:5] offset:2048
	v_cvt_pk_bf16_f32 v198, v22, v23
	v_cvt_pk_bf16_f32 v199, v24, v25
	global_store_dwordx2 v38, v[198:199], s[4:5] offset:2560
	v_cvt_pk_bf16_f32 v200, v26, v27
	v_cvt_pk_bf16_f32 v201, v28, v29
	global_store_dwordx2 v38, v[200:201], s[4:5] offset:3072
	v_cvt_pk_bf16_f32 v202, v42, v43
	v_cvt_pk_bf16_f32 v203, v44, v45
	global_store_dwordx2 v38, v[202:203], s[4:5] offset:3584
	ds_bpermute_b32 v41, v62, v40
	s_waitcnt lgkmcnt(0)
	v_add_f32_e32 v40, v40, v41
	ds_bpermute_b32 v41, v63, v40
	s_waitcnt lgkmcnt(0)
	v_add_f32_e32 v40, v40, v41
	ds_bpermute_b32 v41, v64, v40
	s_waitcnt lgkmcnt(0)
	v_add_f32_e32 v40, v40, v41
	ds_bpermute_b32 v41, v65, v40
	s_waitcnt lgkmcnt(0)
	v_add_f32_e32 v40, v40, v41
	ds_bpermute_b32 v41, v66, v40
	s_waitcnt lgkmcnt(0)
	v_add_f32_e32 v40, v40, v41
	ds_bpermute_b32 v41, v67, v40
	s_and_saveexec_b64 s[4:5], s[40:41]
	s_cbranch_execz .LBB0_1018
	s_add_u32 s8, s2, s6
	s_waitcnt lgkmcnt(0)
	v_add_f32_e32 v0, v40, v41
	s_addc_u32 s9, s3, s7
	global_store_dword v169, v0, s[8:9]
	s_branch .LBB0_1018
